# v56 + MLP-up epilogues: per-row-group counted waits (vmcnt 7..14) instead of one vmcnt(0) after the eight row loads
# baseline (speedup 1.0000x reference)
; #define PG8_STAGE(bufoff, gbase, voff) do { _Pragma("unroll") for (int _i = 0; _i < 2; ++_i) \
;         __builtin_amdgcn_global_load_lds((const unsigned*)((const char*)(gbase) + (voff)[_i]), (LAS unsigned*)(lds + (bufoff) + ldsw + _i * 8192), 16, 0, 0); } while (0)
; #define PG8_LDA(dst, b, h) do { _Pragma("unroll") for (int m = 0; m < 4; ++m) _Pragma("unroll") for (int k = 0; k < 2; ++k) dst[m][k] = *(const LAS bf16x8*)(lds + PG8_SA(b, h) + aoff + m * 2048 + k * 1024); } while (0)
; #define PG8_LDB(dst, b, h) do { _Pragma("unroll") for (int n = 0; n < 2; ++n) _Pragma("unroll") for (int k = 0; k < 2; ++k) dst[n][k] = *(const LAS bf16x8*)(lds + PG8_SB(b, h) + boff + n * 2048 + k * 1024); } while (0)
; #define PG8_WAIT_V(n) asm volatile("s_waitcnt vmcnt(" #n ")" ::: "memory")
; #define PG8_WAIT_L(n) asm volatile("s_waitcnt lgkmcnt(" #n ")" ::: "memory")
; #define PG8_BAR __builtin_amdgcn_s_barrier()
; #define PG8_SCHED __builtin_amdgcn_sched_barrier(0)
; template <class Epi>
; __device__ __forceinline__ void gemm_phase(LAS unsigned char* lds, const Gemm g, const StaticOrder& S, const Epi& E) {
;     ...
;             PG8_LDB(B0, 0, 0); PG8_SCHED; PG8_LDA(At, 0, 0); PG8_STAGE(PG8_SA(1, 1), a1 + hstep, voffA);
;             PG8_WAIT_L(8); PG8_BAR; PG8_WAIT_L(0); PG8_MMA(0, 0, At, B0); PG8_BAR; PG8_SCHED;
;             PG8_LDB(B1, 0, 1); PG8_STAGE(PG8_SB(0, 0), b2, voffB);
;             PG8_BAR; PG8_WAIT_L(0); PG8_MMA(0, 1, At, B1); PG8_BAR;
;             PG8_LDA(At, 0, 1); PG8_STAGE(PG8_SA(0, 0), a2, voffA);
;             PG8_BAR; PG8_WAIT_L(0); PG8_MMA(1, 0, At, B0); PG8_BAR; PG8_SCHED;
;             PG8_STAGE(PG8_SB(0, 1), b2 + hstep, voffB);
;             PG8_WAIT_V(6); PG8_BAR; PG8_MMA(1, 1, At, B1); PG8_BAR;
;             PG8_LDB(B0, 1, 0); PG8_SCHED; PG8_LDA(At, 1, 0); PG8_STAGE(PG8_SA(0, 1), a2 + hstep, voffA);
;             PG8_WAIT_L(8); PG8_BAR; PG8_WAIT_L(0); PG8_MMA(0, 0, At, B0); PG8_BAR; PG8_SCHED;
;             PG8_LDB(B1, 1, 1); PG8_STAGE(PG8_SB(1, 0), b3, voffB);
;             PG8_BAR; PG8_WAIT_L(0); PG8_MMA(0, 1, At, B1); PG8_BAR;
;             PG8_LDA(At, 1, 1); PG8_STAGE(PG8_SA(1, 0), a3, voffA);
;             PG8_BAR; PG8_WAIT_L(0); PG8_MMA(1, 0, At, B0); PG8_BAR; PG8_SCHED;
;             PG8_STAGE(PG8_SB(1, 1), b3 + hstep, voffB);
;             PG8_WAIT_V(6); PG8_BAR; PG8_MMA(1, 1, At, B1); PG8_BAR;
.LBB0_926:
	ds_read_b128 v[144:147], v155
	ds_read_b128 v[148:151], v155 offset:1024
	ds_read_b128 v[160:163], v155 offset:2048
	ds_read_b128 v[164:167], v155 offset:3072
	s_add_u32 s28, s0, 0xfffc0080
	s_addc_u32 s29, s1, -1
	s_cmp_eq_u32 s70, 12
	s_cselect_b32 s31, s21, s29
	s_cselect_b32 s30, s60, s28
	s_cselect_b32 s29, s19, s63
	s_cselect_b32 s28, s61, s62
	v_lshl_add_u64 v[172:173], s[0:1], 0, v[136:137]
	s_add_i32 m0, s27, 0xc000
	ds_read_b128 v[168:171], v156
	ds_read_b128 v[180:183], v156 offset:1024
	ds_read_b128 v[184:187], v156 offset:2048
	ds_read_b128 v[188:191], v156 offset:3072
	ds_read_b128 v[192:195], v156 offset:4096
	ds_read_b128 v[196:199], v156 offset:5120
	ds_read_b128 v[200:203], v156 offset:6144
	ds_read_b128 v[204:207], v156 offset:7168
	global_load_lds_dwordx4 v[172:173], off
	v_lshl_add_u64 v[172:173], s[0:1], 0, v[138:139]
	s_add_i32 m0, s27, 0xe000
	s_nop 0
	global_load_lds_dwordx4 v[172:173], off
	s_waitcnt lgkmcnt(8)
	s_barrier
	s_waitcnt lgkmcnt(0)
	s_setprio 1
	s_waitcnt lgkmcnt(0)
	v_mfma_f32_16x16x32_bf16 v[124:127], v[144:147], v[168:171], v[124:127]
	v_mfma_f32_16x16x32_bf16 v[120:123], v[160:163], v[168:171], v[120:123]
	v_mfma_f32_16x16x32_bf16 v[108:111], v[144:147], v[184:187], v[108:111]
	v_mfma_f32_16x16x32_bf16 v[104:107], v[160:163], v[184:187], v[104:107]
	v_mfma_f32_16x16x32_bf16 v[92:95], v[144:147], v[192:195], v[92:95]
	v_mfma_f32_16x16x32_bf16 v[88:91], v[160:163], v[192:195], v[88:91]
	v_mfma_f32_16x16x32_bf16 v[76:79], v[144:147], v[200:203], v[76:79]
	v_mfma_f32_16x16x32_bf16 v[72:75], v[160:163], v[200:203], v[72:75]
	v_mfma_f32_16x16x32_bf16 v[124:127], v[148:151], v[180:183], v[124:127]
	v_mfma_f32_16x16x32_bf16 v[120:123], v[164:167], v[180:183], v[120:123]
	v_mfma_f32_16x16x32_bf16 v[108:111], v[148:151], v[188:191], v[108:111]
	v_mfma_f32_16x16x32_bf16 v[104:107], v[164:167], v[188:191], v[104:107]
	v_mfma_f32_16x16x32_bf16 v[92:95], v[148:151], v[196:199], v[92:95]
	v_mfma_f32_16x16x32_bf16 v[88:91], v[164:167], v[196:199], v[88:91]
	v_mfma_f32_16x16x32_bf16 v[76:79], v[148:151], v[204:207], v[76:79]
	v_mfma_f32_16x16x32_bf16 v[72:75], v[164:167], v[204:207], v[72:75]
	s_setprio 0
	s_barrier
	s_add_i32 s71, s48, s33
	v_lshl_add_u64 v[172:173], s[28:29], 0, v[130:131]
	s_mov_b32 m0, s71
	ds_read_b128 v[208:211], v157
	ds_read_b128 v[212:215], v157 offset:1024
	ds_read_b128 v[216:219], v157 offset:2048
	ds_read_b128 v[220:223], v157 offset:3072
	global_load_lds_dwordx4 v[172:173], off
	v_lshl_add_u64 v[176:177], s[28:29], 0, v[134:135]
	s_add_i32 m0, s71, 0x2000
	s_nop 0
	global_load_lds_dwordx4 v[176:177], off
	s_barrier
	s_waitcnt lgkmcnt(0)
	s_setprio 1
	s_waitcnt lgkmcnt(0)
	v_mfma_f32_16x16x32_bf16 v[116:119], v[208:211], v[168:171], v[116:119]
	v_mfma_f32_16x16x32_bf16 v[112:115], v[216:219], v[168:171], v[112:115]
	v_mfma_f32_16x16x32_bf16 v[100:103], v[208:211], v[184:187], v[100:103]
	v_mfma_f32_16x16x32_bf16 v[96:99], v[216:219], v[184:187], v[96:99]
	v_mfma_f32_16x16x32_bf16 v[84:87], v[208:211], v[192:195], v[84:87]
	v_mfma_f32_16x16x32_bf16 v[80:83], v[216:219], v[192:195], v[80:83]
	v_mfma_f32_16x16x32_bf16 v[68:71], v[208:211], v[200:203], v[68:71]
	v_mfma_f32_16x16x32_bf16 v[64:67], v[216:219], v[200:203], v[64:67]
	v_mfma_f32_16x16x32_bf16 v[116:119], v[212:215], v[180:183], v[116:119]
	v_mfma_f32_16x16x32_bf16 v[112:115], v[220:223], v[180:183], v[112:115]
	v_mfma_f32_16x16x32_bf16 v[100:103], v[212:215], v[188:191], v[100:103]
	v_mfma_f32_16x16x32_bf16 v[96:99], v[220:223], v[188:191], v[96:99]
	v_mfma_f32_16x16x32_bf16 v[84:87], v[212:215], v[196:199], v[84:87]
	v_mfma_f32_16x16x32_bf16 v[80:83], v[220:223], v[196:199], v[80:83]
	v_mfma_f32_16x16x32_bf16 v[68:71], v[212:215], v[204:207], v[68:71]
	v_mfma_f32_16x16x32_bf16 v[64:67], v[220:223], v[204:207], v[64:67]
	s_setprio 0
	s_mov_b32 m0, s27
	v_lshl_add_u64 v[224:225], s[30:31], 0, v[128:129]
	s_barrier
	ds_read_b128 v[168:171], v156 offset:16384
	ds_read_b128 v[180:183], v156 offset:17408
	ds_read_b128 v[184:187], v156 offset:18432
	ds_read_b128 v[188:191], v156 offset:19456
	ds_read_b128 v[192:195], v156 offset:20480
	ds_read_b128 v[196:199], v156 offset:21504
	ds_read_b128 v[200:203], v156 offset:22528
	ds_read_b128 v[204:207], v156 offset:23552
	global_load_lds_dwordx4 v[224:225], off
	v_lshl_add_u64 v[226:227], s[30:31], 0, v[132:133]
	s_mov_b32 m0, s38
	s_nop 0
	global_load_lds_dwordx4 v[226:227], off
	s_barrier
	s_waitcnt lgkmcnt(0)
	s_setprio 1
	s_waitcnt lgkmcnt(0)
	v_mfma_f32_16x16x32_bf16 v[60:63], v[144:147], v[168:171], v[60:63]
	v_mfma_f32_16x16x32_bf16 v[56:59], v[160:163], v[168:171], v[56:59]
	v_mfma_f32_16x16x32_bf16 v[44:47], v[144:147], v[184:187], v[44:47]
	v_mfma_f32_16x16x32_bf16 v[40:43], v[160:163], v[184:187], v[40:43]
	v_mfma_f32_16x16x32_bf16 v[28:31], v[144:147], v[192:195], v[28:31]
	v_mfma_f32_16x16x32_bf16 v[24:27], v[160:163], v[192:195], v[24:27]
	v_mfma_f32_16x16x32_bf16 v[12:15], v[144:147], v[200:203], v[12:15]
	v_mfma_f32_16x16x32_bf16 v[8:11], v[160:163], v[200:203], v[8:11]
	v_mfma_f32_16x16x32_bf16 v[60:63], v[148:151], v[180:183], v[60:63]
	v_mfma_f32_16x16x32_bf16 v[56:59], v[164:167], v[180:183], v[56:59]
	v_mfma_f32_16x16x32_bf16 v[44:47], v[148:151], v[188:191], v[44:47]
	v_mfma_f32_16x16x32_bf16 v[40:43], v[164:167], v[188:191], v[40:43]
	v_mfma_f32_16x16x32_bf16 v[28:31], v[148:151], v[196:199], v[28:31]
	v_mfma_f32_16x16x32_bf16 v[24:27], v[164:167], v[196:199], v[24:27]
	v_mfma_f32_16x16x32_bf16 v[12:15], v[148:151], v[204:207], v[12:15]
	v_mfma_f32_16x16x32_bf16 v[8:11], v[164:167], v[204:207], v[8:11]
	s_setprio 0
	s_barrier
; #define PG8_STAGE(bufoff, gbase, voff) do { _Pragma("unroll") for (int _i = 0; _i < 2; ++_i) \
;         __builtin_amdgcn_global_load_lds((const unsigned*)((const char*)(gbase) + (voff)[_i]), (LAS unsigned*)(lds + (bufoff) + ldsw + _i * 8192), 16, 0, 0); } while (0)
; #define PG8_LDA(dst, b, h) do { _Pragma("unroll") for (int m = 0; m < 4; ++m) _Pragma("unroll") for (int k = 0; k < 2; ++k) dst[m][k] = *(const LAS bf16x8*)(lds + PG8_SA(b, h) + aoff + m * 2048 + k * 1024); } while (0)
; #define PG8_LDB(dst, b, h) do { _Pragma("unroll") for (int n = 0; n < 2; ++n) _Pragma("unroll") for (int k = 0; k < 2; ++k) dst[n][k] = *(const LAS bf16x8*)(lds + PG8_SB(b, h) + boff + n * 2048 + k * 1024); } while (0)
; #define PG8_WAIT_V(n) asm volatile("s_waitcnt vmcnt(" #n ")" ::: "memory")
; #define PG8_WAIT_L(n) asm volatile("s_waitcnt lgkmcnt(" #n ")" ::: "memory")
; #define PG8_BAR __builtin_amdgcn_s_barrier()
; #define PG8_SCHED __builtin_amdgcn_sched_barrier(0)
; template <class Epi>
; __device__ __forceinline__ void gemm_phase(LAS unsigned char* lds, const Gemm g, const StaticOrder& S, const Epi& E) {
;     ...
;             PG8_LDB(B0, 0, 0); PG8_SCHED; PG8_LDA(At, 0, 0); PG8_STAGE(PG8_SA(1, 1), a1 + hstep, voffA);
;             PG8_WAIT_L(8); PG8_BAR; PG8_WAIT_L(0); PG8_MMA(0, 0, At, B0); PG8_BAR; PG8_SCHED;
;             PG8_LDB(B1, 0, 1); PG8_STAGE(PG8_SB(0, 0), b2, voffB);
;             PG8_BAR; PG8_WAIT_L(0); PG8_MMA(0, 1, At, B1); PG8_BAR;
;             PG8_LDA(At, 0, 1); PG8_STAGE(PG8_SA(0, 0), a2, voffA);
;             PG8_BAR; PG8_WAIT_L(0); PG8_MMA(1, 0, At, B0); PG8_BAR; PG8_SCHED;
;             PG8_STAGE(PG8_SB(0, 1), b2 + hstep, voffB);
;             PG8_WAIT_V(6); PG8_BAR; PG8_MMA(1, 1, At, B1); PG8_BAR;
;             PG8_LDB(B0, 1, 0); PG8_SCHED; PG8_LDA(At, 1, 0); PG8_STAGE(PG8_SA(0, 1), a2 + hstep, voffA);
;             PG8_WAIT_L(8); PG8_BAR; PG8_WAIT_L(0); PG8_MMA(0, 0, At, B0); PG8_BAR; PG8_SCHED;
;             PG8_LDB(B1, 1, 1); PG8_STAGE(PG8_SB(1, 0), b3, voffB);
;             PG8_BAR; PG8_WAIT_L(0); PG8_MMA(0, 1, At, B1); PG8_BAR;
;             PG8_LDA(At, 1, 1); PG8_STAGE(PG8_SA(1, 0), a3, voffA);
;             PG8_BAR; PG8_WAIT_L(0); PG8_MMA(1, 0, At, B0); PG8_BAR; PG8_SCHED;
;             PG8_STAGE(PG8_SB(1, 1), b3 + hstep, voffB);
;             PG8_WAIT_V(6); PG8_BAR; PG8_MMA(1, 1, At, B1); PG8_BAR;
	s_add_u32 s72, s28, 0x40000
	s_addc_u32 s73, s29, 0
	s_add_i32 s71, s49, s33
	v_lshl_add_u64 v[144:145], s[72:73], 0, v[130:131]
	s_mov_b32 m0, s71
	s_nop 0
	global_load_lds_dwordx4 v[144:145], off
	v_lshl_add_u64 v[144:145], s[72:73], 0, v[134:135]
	s_add_i32 m0, s71, 0x2000
	s_nop 0
	global_load_lds_dwordx4 v[144:145], off
	s_waitcnt vmcnt(6)
	s_barrier
	s_setprio 1
	v_mfma_f32_16x16x32_bf16 v[52:55], v[208:211], v[168:171], v[52:55]
	v_mfma_f32_16x16x32_bf16 v[48:51], v[216:219], v[168:171], v[48:51]
	v_mfma_f32_16x16x32_bf16 v[36:39], v[208:211], v[184:187], v[36:39]
	v_mfma_f32_16x16x32_bf16 v[32:35], v[216:219], v[184:187], v[32:35]
	v_mfma_f32_16x16x32_bf16 v[20:23], v[208:211], v[192:195], v[20:23]
	v_mfma_f32_16x16x32_bf16 v[16:19], v[216:219], v[192:195], v[16:19]
	v_mfma_f32_16x16x32_bf16 v[4:7], v[208:211], v[200:203], v[4:7]
	v_mfma_f32_16x16x32_bf16 v[0:3], v[216:219], v[200:203], v[0:3]
	v_mfma_f32_16x16x32_bf16 v[52:55], v[212:215], v[180:183], v[52:55]
	v_mfma_f32_16x16x32_bf16 v[48:51], v[220:223], v[180:183], v[48:51]
	v_mfma_f32_16x16x32_bf16 v[36:39], v[212:215], v[188:191], v[36:39]
	v_mfma_f32_16x16x32_bf16 v[32:35], v[220:223], v[188:191], v[32:35]
	v_mfma_f32_16x16x32_bf16 v[20:23], v[212:215], v[196:199], v[20:23]
	v_mfma_f32_16x16x32_bf16 v[16:19], v[220:223], v[196:199], v[16:19]
	v_mfma_f32_16x16x32_bf16 v[4:7], v[212:215], v[204:207], v[4:7]
	v_mfma_f32_16x16x32_bf16 v[0:3], v[220:223], v[204:207], v[0:3]
	s_setprio 0
	s_add_i32 s71, 0, 0x18000
	v_add_u32_e32 v159, s71, v153
	s_barrier
	ds_read_b128 v[144:147], v159
	ds_read_b128 v[148:151], v159 offset:1024
	ds_read_b128 v[160:163], v159 offset:2048
	ds_read_b128 v[164:167], v159 offset:3072
	s_add_u32 s30, s30, 0x40000
	s_addc_u32 s31, s31, 0
	s_mov_b32 m0, s39
	v_lshl_add_u64 v[208:209], s[30:31], 0, v[128:129]
	ds_read_b128 v[168:171], v156 offset:32768
	ds_read_b128 v[180:183], v156 offset:33792
	ds_read_b128 v[184:187], v156 offset:34816
	ds_read_b128 v[188:191], v156 offset:35840
	ds_read_b128 v[192:195], v156 offset:36864
	ds_read_b128 v[196:199], v156 offset:37888
	ds_read_b128 v[200:203], v156 offset:38912
	ds_read_b128 v[204:207], v156 offset:39936
	global_load_lds_dwordx4 v[208:209], off
	v_lshl_add_u64 v[208:209], s[30:31], 0, v[132:133]
	s_mov_b32 m0, s42
	s_nop 0
	global_load_lds_dwordx4 v[208:209], off
	s_waitcnt lgkmcnt(8)
	s_barrier
	s_waitcnt lgkmcnt(0)
	s_setprio 1
	s_waitcnt lgkmcnt(0)
	v_mfma_f32_16x16x32_bf16 v[124:127], v[144:147], v[168:171], v[124:127]
	v_mfma_f32_16x16x32_bf16 v[120:123], v[160:163], v[168:171], v[120:123]
	v_mfma_f32_16x16x32_bf16 v[108:111], v[144:147], v[184:187], v[108:111]
	v_mfma_f32_16x16x32_bf16 v[104:107], v[160:163], v[184:187], v[104:107]
	v_mfma_f32_16x16x32_bf16 v[92:95], v[144:147], v[192:195], v[92:95]
	v_mfma_f32_16x16x32_bf16 v[88:91], v[160:163], v[192:195], v[88:91]
	v_mfma_f32_16x16x32_bf16 v[76:79], v[144:147], v[200:203], v[76:79]
	v_mfma_f32_16x16x32_bf16 v[72:75], v[160:163], v[200:203], v[72:75]
	v_mfma_f32_16x16x32_bf16 v[124:127], v[148:151], v[180:183], v[124:127]
	v_mfma_f32_16x16x32_bf16 v[120:123], v[164:167], v[180:183], v[120:123]
	v_mfma_f32_16x16x32_bf16 v[108:111], v[148:151], v[188:191], v[108:111]
	v_mfma_f32_16x16x32_bf16 v[104:107], v[164:167], v[188:191], v[104:107]
	v_mfma_f32_16x16x32_bf16 v[92:95], v[148:151], v[196:199], v[92:95]
	v_mfma_f32_16x16x32_bf16 v[88:91], v[164:167], v[196:199], v[88:91]
	v_mfma_f32_16x16x32_bf16 v[76:79], v[148:151], v[204:207], v[76:79]
	v_mfma_f32_16x16x32_bf16 v[72:75], v[164:167], v[204:207], v[72:75]
	s_setprio 0
	s_barrier
	s_add_i32 s30, 0, 0x1c000
	s_add_i32 s31, s71, s33
	v_add_u32_e32 v159, s30, v153
	v_lshl_add_u64 v[172:173], v[172:173], 0, s[6:7]
	s_mov_b32 m0, s31
	ds_read_b128 v[208:211], v159
	ds_read_b128 v[212:215], v159 offset:1024
	ds_read_b128 v[216:219], v159 offset:2048
	ds_read_b128 v[220:223], v159 offset:3072
	global_load_lds_dwordx4 v[172:173], off
	v_lshl_add_u64 v[172:173], v[176:177], 0, s[6:7]
	s_add_i32 m0, s31, 0x2000
	s_nop 0
	global_load_lds_dwordx4 v[172:173], off
	s_barrier
	s_waitcnt lgkmcnt(0)
	s_setprio 1
	s_waitcnt lgkmcnt(0)
	v_mfma_f32_16x16x32_bf16 v[116:119], v[208:211], v[168:171], v[116:119]
	v_mfma_f32_16x16x32_bf16 v[112:115], v[216:219], v[168:171], v[112:115]
	v_mfma_f32_16x16x32_bf16 v[100:103], v[208:211], v[184:187], v[100:103]
	v_mfma_f32_16x16x32_bf16 v[96:99], v[216:219], v[184:187], v[96:99]
	v_mfma_f32_16x16x32_bf16 v[84:87], v[208:211], v[192:195], v[84:87]
	v_mfma_f32_16x16x32_bf16 v[80:83], v[216:219], v[192:195], v[80:83]
	v_mfma_f32_16x16x32_bf16 v[68:71], v[208:211], v[200:203], v[68:71]
	v_mfma_f32_16x16x32_bf16 v[64:67], v[216:219], v[200:203], v[64:67]
	v_mfma_f32_16x16x32_bf16 v[116:119], v[212:215], v[180:183], v[116:119]
	v_mfma_f32_16x16x32_bf16 v[112:115], v[220:223], v[180:183], v[112:115]
	v_mfma_f32_16x16x32_bf16 v[100:103], v[212:215], v[188:191], v[100:103]
	v_mfma_f32_16x16x32_bf16 v[96:99], v[220:223], v[188:191], v[96:99]
	v_mfma_f32_16x16x32_bf16 v[84:87], v[212:215], v[196:199], v[84:87]
	v_mfma_f32_16x16x32_bf16 v[80:83], v[220:223], v[196:199], v[80:83]
	v_mfma_f32_16x16x32_bf16 v[68:71], v[212:215], v[204:207], v[68:71]
	v_mfma_f32_16x16x32_bf16 v[64:67], v[220:223], v[204:207], v[64:67]
	s_setprio 0
	s_mov_b32 m0, s44
	v_lshl_add_u64 v[172:173], v[224:225], 0, s[6:7]
	s_barrier
	ds_read_b128 v[168:171], v156 offset:49152
	ds_read_b128 v[180:183], v156 offset:50176
	ds_read_b128 v[184:187], v156 offset:51200
	ds_read_b128 v[188:191], v156 offset:52224
	ds_read_b128 v[192:195], v156 offset:53248
	ds_read_b128 v[196:199], v156 offset:54272
	ds_read_b128 v[200:203], v156 offset:55296
	ds_read_b128 v[204:207], v156 offset:56320
	global_load_lds_dwordx4 v[172:173], off
	v_lshl_add_u64 v[172:173], v[226:227], 0, s[6:7]
	s_mov_b32 m0, s45
	s_nop 0
	global_load_lds_dwordx4 v[172:173], off
	s_barrier
; DI unsigned pk2(float a, float b) { f32x2 v = {a, b}; hbf2 r = __builtin_convertvector(v, hbf2); return __builtin_bit_cast(unsigned, r); }
; #define PG8_STAGE(bufoff, gbase, voff) do { _Pragma("unroll") for (int _i = 0; _i < 2; ++_i) \
;         __builtin_amdgcn_global_load_lds((const unsigned*)((const char*)(gbase) + (voff)[_i]), (LAS unsigned*)(lds + (bufoff) + ldsw + _i * 8192), 16, 0, 0); } while (0)
; #define PG8_WAIT_V(n) asm volatile("s_waitcnt vmcnt(" #n ")" ::: "memory")
; #define PG8_WAIT_L(n) asm volatile("s_waitcnt lgkmcnt(" #n ")" ::: "memory")
; #define PG8_BAR __builtin_amdgcn_s_barrier()
; template <class Epi>
; __device__ __forceinline__ void gemm_phase(LAS unsigned char* lds, const Gemm g, const StaticOrder& S, const Epi& E) {
;     ...
;             PG8_WAIT_V(6); PG8_BAR; PG8_MMA(1, 1, At, B1); PG8_BAR;
;             PG8_LDB(B0, 1, 0); PG8_SCHED; PG8_LDA(At, 1, 0); PG8_STAGE(PG8_SA(0, 1), a2 + hstep, voffA);
;             PG8_WAIT_L(8); PG8_BAR; PG8_WAIT_L(0); PG8_MMA(0, 0, At, B0); PG8_BAR; PG8_SCHED;
;             PG8_LDB(B1, 1, 1); PG8_STAGE(PG8_SB(1, 0), b3, voffB);
;             PG8_BAR; PG8_WAIT_L(0); PG8_MMA(0, 1, At, B1); PG8_BAR;
;             PG8_LDA(At, 1, 1); PG8_STAGE(PG8_SA(1, 0), a3, voffA);
;             PG8_BAR; PG8_WAIT_L(0); PG8_MMA(1, 0, At, B0); PG8_BAR; PG8_SCHED;
;             PG8_STAGE(PG8_SB(1, 1), b3 + hstep, voffB);
;             PG8_WAIT_V(6); PG8_BAR; PG8_MMA(1, 1, At, B1); PG8_BAR;
;     DI void operator()(const f32x4 (&acc)[2][2][4][2], const Unit& u, int wr, int wc, int fr, int fq) const {
;     ...
; #pragma unroll
;         for (int ai = 0; ai < 2; ++ai)
; #pragma unroll
;             for (int m = 0; m < 4; ++m) {
;                 const int r = row0 + ai * 128 + m * 16;
;                 const float rstd = rsqrtf(ss[r] * (1.0f / 1024.0f) + EPS);
;                 bf16_t* rowp = HID + (size_t)r * 4096 + col0;
; #pragma unroll
;                 for (int bj = 0; bj < 2; ++bj) {
;                     f32x4 v0 = acc[ai][bj][m][0] * rstd, v1 = acc[ai][bj][m][1] * rstd;
; #pragma unroll
;                     for (int j = 0; j < 4; ++j) { float a = fmaxf(v0[j], 0.f), b = fmaxf(v1[j], 0.f); v0[j] = a * a; v1[j] = b * b; }
;                     u32x4 w; w.x = pk2(v0[0], v0[1]); w.y = pk2(v0[2], v0[3]); w.z = pk2(v1[0], v1[1]); w.w = pk2(v1[2], v1[3]);
;                     *(u32x4*)(rowp + bj * 128) = w;
;                 }
	s_waitcnt lgkmcnt(0)
	s_setprio 1
	s_waitcnt lgkmcnt(0)
	v_mfma_f32_16x16x32_bf16 v[60:63], v[144:147], v[168:171], v[60:63]
	v_mfma_f32_16x16x32_bf16 v[56:59], v[160:163], v[168:171], v[56:59]
	v_mfma_f32_16x16x32_bf16 v[44:47], v[144:147], v[184:187], v[44:47]
	v_mfma_f32_16x16x32_bf16 v[40:43], v[160:163], v[184:187], v[40:43]
	v_mfma_f32_16x16x32_bf16 v[28:31], v[144:147], v[192:195], v[28:31]
	v_mfma_f32_16x16x32_bf16 v[24:27], v[160:163], v[192:195], v[24:27]
	v_mfma_f32_16x16x32_bf16 v[12:15], v[144:147], v[200:203], v[12:15]
	v_mfma_f32_16x16x32_bf16 v[8:11], v[160:163], v[200:203], v[8:11]
	v_mfma_f32_16x16x32_bf16 v[60:63], v[148:151], v[180:183], v[60:63]
	v_mfma_f32_16x16x32_bf16 v[56:59], v[164:167], v[180:183], v[56:59]
	v_mfma_f32_16x16x32_bf16 v[44:47], v[148:151], v[188:191], v[44:47]
	v_mfma_f32_16x16x32_bf16 v[40:43], v[164:167], v[188:191], v[40:43]
	v_mfma_f32_16x16x32_bf16 v[28:31], v[148:151], v[196:199], v[28:31]
	v_mfma_f32_16x16x32_bf16 v[24:27], v[164:167], v[196:199], v[24:27]
	v_mfma_f32_16x16x32_bf16 v[12:15], v[148:151], v[204:207], v[12:15]
	v_mfma_f32_16x16x32_bf16 v[8:11], v[164:167], v[204:207], v[8:11]
	s_setprio 0
	s_barrier
	s_add_u32 s28, s28, 0x40080
	s_addc_u32 s29, s29, 0
	s_add_i32 s30, s30, s33
	v_lshl_add_u64 v[144:145], s[28:29], 0, v[130:131]
	s_mov_b32 m0, s30
	s_nop 0
	global_load_lds_dwordx4 v[144:145], off
	v_lshl_add_u64 v[144:145], s[28:29], 0, v[134:135]
	s_add_i32 m0, s30, 0x2000
	s_nop 0
	global_load_lds_dwordx4 v[144:145], off
	s_waitcnt vmcnt(6)
	s_barrier
	s_setprio 1
	v_mfma_f32_16x16x32_bf16 v[52:55], v[208:211], v[168:171], v[52:55]
	v_mfma_f32_16x16x32_bf16 v[48:51], v[216:219], v[168:171], v[48:51]
	v_mfma_f32_16x16x32_bf16 v[36:39], v[208:211], v[184:187], v[36:39]
	v_mfma_f32_16x16x32_bf16 v[32:35], v[216:219], v[184:187], v[32:35]
	v_mfma_f32_16x16x32_bf16 v[20:23], v[208:211], v[192:195], v[20:23]
	v_mfma_f32_16x16x32_bf16 v[16:19], v[216:219], v[192:195], v[16:19]
	v_mfma_f32_16x16x32_bf16 v[4:7], v[208:211], v[200:203], v[4:7]
	v_mfma_f32_16x16x32_bf16 v[0:3], v[216:219], v[200:203], v[0:3]
	v_mfma_f32_16x16x32_bf16 v[52:55], v[212:215], v[180:183], v[52:55]
	v_mfma_f32_16x16x32_bf16 v[48:51], v[220:223], v[180:183], v[48:51]
	v_mfma_f32_16x16x32_bf16 v[36:39], v[212:215], v[188:191], v[36:39]
	v_mfma_f32_16x16x32_bf16 v[32:35], v[220:223], v[188:191], v[32:35]
	v_mfma_f32_16x16x32_bf16 v[20:23], v[212:215], v[196:199], v[20:23]
	v_mfma_f32_16x16x32_bf16 v[16:19], v[220:223], v[196:199], v[16:19]
	v_mfma_f32_16x16x32_bf16 v[4:7], v[212:215], v[204:207], v[4:7]
	v_mfma_f32_16x16x32_bf16 v[0:3], v[220:223], v[204:207], v[0:3]
	s_setprio 0
	s_add_i32 s70, s70, 2
	s_add_u32 s0, s0, 0x100
	s_addc_u32 s1, s1, 0
	s_add_u32 s62, s62, 0x100
	s_addc_u32 s63, s63, 0
	s_cmp_gt_u32 s70, 13
	s_barrier
	s_cbranch_scc0 .LBB0_926
	v_lshl_add_u32 v148, s26, 8, v152
	v_ashrrev_i32_e32 v149, 31, v148
	v_lshl_add_u64 v[144:145], v[148:149], 2, s[94:95]
	global_load_dword v159, v[144:145], off
	global_load_dword v209, v[144:145], off offset:64
	global_load_dword v210, v[144:145], off offset:128
	global_load_dword v211, v[144:145], off offset:192
	global_load_dword v212, v[144:145], off offset:512
	global_load_dword v213, v[144:145], off offset:576
	global_load_dword v214, v[144:145], off offset:640
	global_load_dword v215, v[144:145], off offset:704
	v_lshl_or_b32 v146, s59, 8, v154
	v_ashrrev_i32_e32 v147, 31, v146
	v_lshlrev_b64 v[150:151], 1, v[146:147]
	v_lshlrev_b64 v[162:163], 13, v[148:149]
	v_or_b32_e32 v160, 16, v148
	v_ashrrev_i32_e32 v161, 31, v160
	s_mov_b32 s59, s18
	s_mov_b32 s26, s20
	s_mov_b64 s[28:29], s[24:25]
	s_mov_b64 s[30:31], s[22:23]
	s_waitcnt vmcnt(7)
	v_fmamk_f32 v146, v159, 0x3a800000, v158
	v_mul_f32_e32 v147, 0x4b800000, v146
	v_cmp_gt_f32_e32 vcc, s50, v146
	s_nop 1
	v_cndmask_b32_e32 v146, v146, v147, vcc
	v_rsq_f32_e32 v149, v146
	v_lshl_add_u64 v[146:147], s[34:35], 0, v[162:163]
	v_lshl_add_u64 v[146:147], v[146:147], 0, v[150:151]
	v_lshl_add_u64 v[162:163], v[160:161], 2, s[94:95]
	v_mul_f32_e32 v159, 0x45800000, v149
	v_cndmask_b32_e32 v164, v149, v159, vcc
	v_pk_mul_f32 v[126:127], v[126:127], v[164:165] op_sel_hi:[1,0]
	v_pk_mul_f32 v[124:125], v[124:125], v[164:165] op_sel_hi:[1,0]
	v_pk_mul_f32 v[122:123], v[122:123], v[164:165] op_sel_hi:[1,0]
	v_pk_mul_f32 v[120:121], v[120:121], v[164:165] op_sel_hi:[1,0]
	v_pk_mul_f32 v[118:119], v[118:119], v[164:165] op_sel_hi:[1,0]
	v_pk_mul_f32 v[116:117], v[116:117], v[164:165] op_sel_hi:[1,0]
	v_pk_mul_f32 v[114:115], v[114:115], v[164:165] op_sel_hi:[1,0]
	v_pk_mul_f32 v[112:113], v[112:113], v[164:165] op_sel_hi:[1,0]
	v_max_f32_e32 v124, 0, v124
	v_max_f32_e32 v120, 0, v120
	v_max_f32_e32 v125, 0, v125
	v_max_f32_e32 v121, 0, v121
	v_max_f32_e32 v126, 0, v126
	v_max_f32_e32 v122, 0, v122
	v_max_f32_e32 v127, 0, v127
	v_max_f32_e32 v123, 0, v123
	v_max_f32_e32 v116, 0, v116
	v_max_f32_e32 v112, 0, v112
	v_max_f32_e32 v117, 0, v117
	v_max_f32_e32 v113, 0, v113
	v_max_f32_e32 v118, 0, v118
	v_max_f32_e32 v114, 0, v114
	v_max_f32_e32 v119, 0, v119
	v_max_f32_e32 v115, 0, v115
	v_pk_mul_f32 v[124:125], v[124:125], v[124:125]
	v_pk_mul_f32 v[120:121], v[120:121], v[120:121]
	v_pk_mul_f32 v[126:127], v[126:127], v[126:127]
	v_pk_mul_f32 v[122:123], v[122:123], v[122:123]
	v_pk_mul_f32 v[116:117], v[116:117], v[116:117]
	v_pk_mul_f32 v[164:165], v[112:113], v[112:113]
	v_pk_mul_f32 v[118:119], v[118:119], v[118:119]
	v_pk_mul_f32 v[166:167], v[114:115], v[114:115]
	v_cvt_pk_bf16_f32 v112, v124, v125
	v_cvt_pk_bf16_f32 v113, v126, v127
	v_cvt_pk_bf16_f32 v114, v120, v121
	v_cvt_pk_bf16_f32 v115, v122, v123
	v_cvt_pk_bf16_f32 v116, v116, v117
	v_cvt_pk_bf16_f32 v117, v118, v119
	v_cvt_pk_bf16_f32 v118, v164, v165
	v_cvt_pk_bf16_f32 v119, v166, v167
	global_store_dwordx4 v[146:147], v[112:115], off
	global_store_dwordx4 v[146:147], v[116:119], off offset:256
	s_nop 0
	v_lshlrev_b64 v[114:115], 13, v[160:161]
	v_or_b32_e32 v112, 32, v148
	v_lshl_add_u64 v[114:115], s[34:35], 0, v[114:115]
	v_ashrrev_i32_e32 v113, 31, v112
	v_lshl_add_u64 v[114:115], v[114:115], 0, v[150:151]
	s_nop 1
	s_waitcnt vmcnt(8)
; DI unsigned pk2(float a, float b) { f32x2 v = {a, b}; hbf2 r = __builtin_convertvector(v, hbf2); return __builtin_bit_cast(unsigned, r); }
;     DI void operator()(const f32x4 (&acc)[2][2][4][2], const Unit& u, int wr, int wc, int fr, int fq) const {
;     ...
; #pragma unroll
;         for (int ai = 0; ai < 2; ++ai)
; #pragma unroll
;             for (int m = 0; m < 4; ++m) {
;                 const int r = row0 + ai * 128 + m * 16;
;                 const float rstd = rsqrtf(ss[r] * (1.0f / 1024.0f) + EPS);
;                 bf16_t* rowp = HID + (size_t)r * 4096 + col0;
; #pragma unroll
;                 for (int bj = 0; bj < 2; ++bj) {
;                     f32x4 v0 = acc[ai][bj][m][0] * rstd, v1 = acc[ai][bj][m][1] * rstd;
; #pragma unroll
;                     for (int j = 0; j < 4; ++j) { float a = fmaxf(v0[j], 0.f), b = fmaxf(v1[j], 0.f); v0[j] = a * a; v1[j] = b * b; }
;                     u32x4 w; w.x = pk2(v0[0], v0[1]); w.y = pk2(v0[2], v0[3]); w.z = pk2(v1[0], v1[1]); w.w = pk2(v1[2], v1[3]);
;                     *(u32x4*)(rowp + bj * 128) = w;
;                 }
	v_mov_b32_e32 v116, v209
	v_fmamk_f32 v116, v116, 0x3a800000, v158
	v_mul_f32_e32 v117, 0x4b800000, v116
	v_cmp_gt_f32_e32 vcc, s50, v116
	s_nop 1
	v_cndmask_b32_e32 v116, v116, v117, vcc
	v_rsq_f32_e32 v118, v116
	v_lshl_add_u64 v[116:117], v[112:113], 2, s[94:95]
	v_mul_f32_e32 v119, 0x45800000, v118
	v_cndmask_b32_e32 v118, v118, v119, vcc
	v_pk_mul_f32 v[110:111], v[110:111], v[118:119] op_sel_hi:[1,0]
	v_pk_mul_f32 v[108:109], v[108:109], v[118:119] op_sel_hi:[1,0]
	v_pk_mul_f32 v[106:107], v[106:107], v[118:119] op_sel_hi:[1,0]
	v_pk_mul_f32 v[104:105], v[104:105], v[118:119] op_sel_hi:[1,0]
	v_pk_mul_f32 v[102:103], v[102:103], v[118:119] op_sel_hi:[1,0]
	v_pk_mul_f32 v[100:101], v[100:101], v[118:119] op_sel_hi:[1,0]
	v_pk_mul_f32 v[98:99], v[98:99], v[118:119] op_sel_hi:[1,0]
	v_pk_mul_f32 v[96:97], v[96:97], v[118:119] op_sel_hi:[1,0]
	v_max_f32_e32 v108, 0, v108
	v_max_f32_e32 v104, 0, v104
	v_max_f32_e32 v109, 0, v109
	v_max_f32_e32 v105, 0, v105
	v_max_f32_e32 v110, 0, v110
	v_max_f32_e32 v106, 0, v106
	v_max_f32_e32 v111, 0, v111
	v_max_f32_e32 v107, 0, v107
	v_max_f32_e32 v100, 0, v100
	v_max_f32_e32 v96, 0, v96
	v_max_f32_e32 v101, 0, v101
	v_max_f32_e32 v97, 0, v97
	v_max_f32_e32 v102, 0, v102
	v_max_f32_e32 v98, 0, v98
	v_max_f32_e32 v103, 0, v103
	v_max_f32_e32 v99, 0, v99
	v_pk_mul_f32 v[108:109], v[108:109], v[108:109]
	v_pk_mul_f32 v[104:105], v[104:105], v[104:105]
	v_pk_mul_f32 v[110:111], v[110:111], v[110:111]
	v_pk_mul_f32 v[106:107], v[106:107], v[106:107]
	v_pk_mul_f32 v[100:101], v[100:101], v[100:101]
	v_pk_mul_f32 v[118:119], v[96:97], v[96:97]
	v_pk_mul_f32 v[102:103], v[102:103], v[102:103]
	v_pk_mul_f32 v[120:121], v[98:99], v[98:99]
	v_cvt_pk_bf16_f32 v96, v108, v109
	v_cvt_pk_bf16_f32 v97, v110, v111
	v_cvt_pk_bf16_f32 v98, v104, v105
	v_cvt_pk_bf16_f32 v99, v106, v107
	v_cvt_pk_bf16_f32 v100, v100, v101
	v_cvt_pk_bf16_f32 v101, v102, v103
	v_cvt_pk_bf16_f32 v102, v118, v119
	v_cvt_pk_bf16_f32 v103, v120, v121
	global_store_dwordx4 v[114:115], v[96:99], off
	global_store_dwordx4 v[114:115], v[100:103], off offset:256
	s_nop 0
	v_lshlrev_b64 v[98:99], 13, v[112:113]
	v_or_b32_e32 v96, 48, v148
	v_lshl_add_u64 v[98:99], s[34:35], 0, v[98:99]
	v_ashrrev_i32_e32 v97, 31, v96
	v_lshl_add_u64 v[98:99], v[98:99], 0, v[150:151]
	s_nop 1
	s_waitcnt vmcnt(9)
	v_mov_b32_e32 v100, v210
	v_fmamk_f32 v100, v100, 0x3a800000, v158
	v_mul_f32_e32 v101, 0x4b800000, v100
	v_cmp_gt_f32_e32 vcc, s50, v100
	s_nop 1
	v_cndmask_b32_e32 v100, v100, v101, vcc
	v_rsq_f32_e32 v102, v100
	v_lshl_add_u64 v[100:101], v[96:97], 2, s[94:95]
	v_mul_f32_e32 v103, 0x45800000, v102
	v_cndmask_b32_e32 v102, v102, v103, vcc
	v_pk_mul_f32 v[94:95], v[94:95], v[102:103] op_sel_hi:[1,0]
	v_pk_mul_f32 v[92:93], v[92:93], v[102:103] op_sel_hi:[1,0]
	v_pk_mul_f32 v[90:91], v[90:91], v[102:103] op_sel_hi:[1,0]
	v_pk_mul_f32 v[88:89], v[88:89], v[102:103] op_sel_hi:[1,0]
	v_pk_mul_f32 v[86:87], v[86:87], v[102:103] op_sel_hi:[1,0]
	v_pk_mul_f32 v[84:85], v[84:85], v[102:103] op_sel_hi:[1,0]
	v_pk_mul_f32 v[82:83], v[82:83], v[102:103] op_sel_hi:[1,0]
	v_pk_mul_f32 v[80:81], v[80:81], v[102:103] op_sel_hi:[1,0]
	v_max_f32_e32 v92, 0, v92
	v_max_f32_e32 v88, 0, v88
	v_max_f32_e32 v93, 0, v93
	v_max_f32_e32 v89, 0, v89
	v_max_f32_e32 v94, 0, v94
	v_max_f32_e32 v90, 0, v90
	v_max_f32_e32 v95, 0, v95
	v_max_f32_e32 v91, 0, v91
	v_max_f32_e32 v84, 0, v84
	v_max_f32_e32 v80, 0, v80
	v_max_f32_e32 v85, 0, v85
	v_max_f32_e32 v81, 0, v81
	v_max_f32_e32 v86, 0, v86
	v_max_f32_e32 v82, 0, v82
	v_max_f32_e32 v87, 0, v87
	v_max_f32_e32 v83, 0, v83
	v_pk_mul_f32 v[92:93], v[92:93], v[92:93]
	v_pk_mul_f32 v[88:89], v[88:89], v[88:89]
	v_pk_mul_f32 v[94:95], v[94:95], v[94:95]
	v_pk_mul_f32 v[90:91], v[90:91], v[90:91]
	v_pk_mul_f32 v[84:85], v[84:85], v[84:85]
	v_pk_mul_f32 v[102:103], v[80:81], v[80:81]
	v_pk_mul_f32 v[86:87], v[86:87], v[86:87]
	v_pk_mul_f32 v[104:105], v[82:83], v[82:83]
	v_cvt_pk_bf16_f32 v80, v92, v93
	v_cvt_pk_bf16_f32 v81, v94, v95
	v_cvt_pk_bf16_f32 v82, v88, v89
	v_cvt_pk_bf16_f32 v83, v90, v91
	v_cvt_pk_bf16_f32 v84, v84, v85
	v_cvt_pk_bf16_f32 v85, v86, v87
	v_cvt_pk_bf16_f32 v86, v102, v103
	v_cvt_pk_bf16_f32 v87, v104, v105
	global_store_dwordx4 v[98:99], v[80:83], off
	global_store_dwordx4 v[98:99], v[84:87], off offset:256
	s_nop 0
	s_nop 1
	s_waitcnt vmcnt(10)
	v_mov_b32_e32 v80, v211
	v_fmamk_f32 v80, v80, 0x3a800000, v158
	v_mul_f32_e32 v81, 0x4b800000, v80
	v_cmp_gt_f32_e32 vcc, s50, v80
	s_nop 1
	v_cndmask_b32_e32 v80, v80, v81, vcc
	v_rsq_f32_e32 v82, v80
	v_lshlrev_b64 v[80:81], 13, v[96:97]
	v_lshl_add_u64 v[80:81], s[34:35], 0, v[80:81]
	v_lshl_add_u64 v[80:81], v[80:81], 0, v[150:151]
	v_mul_f32_e32 v83, 0x45800000, v82
	v_cndmask_b32_e32 v82, v82, v83, vcc
	v_pk_mul_f32 v[78:79], v[78:79], v[82:83] op_sel_hi:[1,0]
	v_pk_mul_f32 v[76:77], v[76:77], v[82:83] op_sel_hi:[1,0]
	v_pk_mul_f32 v[74:75], v[74:75], v[82:83] op_sel_hi:[1,0]
	v_pk_mul_f32 v[72:73], v[72:73], v[82:83] op_sel_hi:[1,0]
	v_pk_mul_f32 v[70:71], v[70:71], v[82:83] op_sel_hi:[1,0]
	v_pk_mul_f32 v[68:69], v[68:69], v[82:83] op_sel_hi:[1,0]
	v_pk_mul_f32 v[66:67], v[66:67], v[82:83] op_sel_hi:[1,0]
	v_pk_mul_f32 v[64:65], v[64:65], v[82:83] op_sel_hi:[1,0]
	v_max_f32_e32 v76, 0, v76
	v_max_f32_e32 v72, 0, v72
	v_max_f32_e32 v77, 0, v77
	v_max_f32_e32 v73, 0, v73
	v_max_f32_e32 v78, 0, v78
	v_max_f32_e32 v74, 0, v74
	v_max_f32_e32 v79, 0, v79
	v_max_f32_e32 v75, 0, v75
	v_max_f32_e32 v68, 0, v68
	v_max_f32_e32 v64, 0, v64
	v_max_f32_e32 v69, 0, v69
	v_max_f32_e32 v65, 0, v65
	v_max_f32_e32 v70, 0, v70
	v_max_f32_e32 v66, 0, v66
	v_max_f32_e32 v71, 0, v71
	v_max_f32_e32 v67, 0, v67
	v_pk_mul_f32 v[76:77], v[76:77], v[76:77]
	v_pk_mul_f32 v[72:73], v[72:73], v[72:73]
	v_pk_mul_f32 v[78:79], v[78:79], v[78:79]
	v_pk_mul_f32 v[74:75], v[74:75], v[74:75]
	v_pk_mul_f32 v[68:69], v[68:69], v[68:69]
	v_pk_mul_f32 v[82:83], v[64:65], v[64:65]
	v_pk_mul_f32 v[70:71], v[70:71], v[70:71]
	v_pk_mul_f32 v[84:85], v[66:67], v[66:67]
	v_cvt_pk_bf16_f32 v64, v76, v77
	v_cvt_pk_bf16_f32 v65, v78, v79
	v_cvt_pk_bf16_f32 v66, v72, v73
	v_cvt_pk_bf16_f32 v67, v74, v75
	v_cvt_pk_bf16_f32 v68, v68, v69
	v_cvt_pk_bf16_f32 v69, v70, v71
	v_cvt_pk_bf16_f32 v70, v82, v83
	v_cvt_pk_bf16_f32 v71, v84, v85
	global_store_dwordx4 v[80:81], v[64:67], off
	global_store_dwordx4 v[80:81], v[68:71], off offset:256
	s_nop 0
	v_lshl_add_u64 v[64:65], v[146:147], 0, s[8:9]
	s_nop 1
	s_waitcnt vmcnt(11)
; DI unsigned pk2(float a, float b) { f32x2 v = {a, b}; hbf2 r = __builtin_convertvector(v, hbf2); return __builtin_bit_cast(unsigned, r); }
;     DI void operator()(const f32x4 (&acc)[2][2][4][2], const Unit& u, int wr, int wc, int fr, int fq) const {
;     ...
; #pragma unroll
;         for (int ai = 0; ai < 2; ++ai)
; #pragma unroll
;             for (int m = 0; m < 4; ++m) {
;                 const int r = row0 + ai * 128 + m * 16;
;                 const float rstd = rsqrtf(ss[r] * (1.0f / 1024.0f) + EPS);
;                 bf16_t* rowp = HID + (size_t)r * 4096 + col0;
; #pragma unroll
;                 for (int bj = 0; bj < 2; ++bj) {
;                     f32x4 v0 = acc[ai][bj][m][0] * rstd, v1 = acc[ai][bj][m][1] * rstd;
; #pragma unroll
;                     for (int j = 0; j < 4; ++j) { float a = fmaxf(v0[j], 0.f), b = fmaxf(v1[j], 0.f); v0[j] = a * a; v1[j] = b * b; }
;                     u32x4 w; w.x = pk2(v0[0], v0[1]); w.y = pk2(v0[2], v0[3]); w.z = pk2(v1[0], v1[1]); w.w = pk2(v1[2], v1[3]);
;                     *(u32x4*)(rowp + bj * 128) = w;
;                 }
	v_mov_b32_e32 v66, v212
	v_fmamk_f32 v66, v66, 0x3a800000, v158
	v_mul_f32_e32 v67, 0x4b800000, v66
	v_cmp_gt_f32_e32 vcc, s50, v66
	s_nop 1
	v_cndmask_b32_e32 v66, v66, v67, vcc
	v_rsq_f32_e32 v68, v66
	v_add_co_u32_e64 v66, s[0:1], s51, v146
	v_mul_f32_e32 v69, 0x45800000, v68
	v_cndmask_b32_e32 v68, v68, v69, vcc
	v_pk_mul_f32 v[62:63], v[62:63], v[68:69] op_sel_hi:[1,0]
	v_pk_mul_f32 v[60:61], v[60:61], v[68:69] op_sel_hi:[1,0]
	v_pk_mul_f32 v[58:59], v[58:59], v[68:69] op_sel_hi:[1,0]
	v_pk_mul_f32 v[56:57], v[56:57], v[68:69] op_sel_hi:[1,0]
	v_pk_mul_f32 v[54:55], v[54:55], v[68:69] op_sel_hi:[1,0]
	v_pk_mul_f32 v[52:53], v[52:53], v[68:69] op_sel_hi:[1,0]
	v_pk_mul_f32 v[50:51], v[50:51], v[68:69] op_sel_hi:[1,0]
	v_pk_mul_f32 v[48:49], v[48:49], v[68:69] op_sel_hi:[1,0]
	v_max_f32_e32 v60, 0, v60
	v_max_f32_e32 v56, 0, v56
	v_max_f32_e32 v61, 0, v61
	v_max_f32_e32 v57, 0, v57
	v_max_f32_e32 v62, 0, v62
	v_max_f32_e32 v58, 0, v58
	v_max_f32_e32 v63, 0, v63
	v_max_f32_e32 v59, 0, v59
	v_max_f32_e32 v52, 0, v52
	v_max_f32_e32 v48, 0, v48
	v_max_f32_e32 v53, 0, v53
	v_max_f32_e32 v49, 0, v49
	v_max_f32_e32 v54, 0, v54
	v_max_f32_e32 v50, 0, v50
	v_max_f32_e32 v55, 0, v55
	v_max_f32_e32 v51, 0, v51
	v_pk_mul_f32 v[60:61], v[60:61], v[60:61]
	v_pk_mul_f32 v[56:57], v[56:57], v[56:57]
	v_pk_mul_f32 v[62:63], v[62:63], v[62:63]
	v_pk_mul_f32 v[58:59], v[58:59], v[58:59]
	v_addc_co_u32_e64 v67, s[0:1], 0, v147, s[0:1]
	v_pk_mul_f32 v[52:53], v[52:53], v[52:53]
	v_pk_mul_f32 v[68:69], v[48:49], v[48:49]
	v_pk_mul_f32 v[54:55], v[54:55], v[54:55]
	v_pk_mul_f32 v[70:71], v[50:51], v[50:51]
	v_cvt_pk_bf16_f32 v48, v60, v61
	v_cvt_pk_bf16_f32 v49, v62, v63
	v_cvt_pk_bf16_f32 v50, v56, v57
	v_cvt_pk_bf16_f32 v51, v58, v59
	v_cvt_pk_bf16_f32 v52, v52, v53
	v_cvt_pk_bf16_f32 v53, v54, v55
	v_cvt_pk_bf16_f32 v54, v68, v69
	v_cvt_pk_bf16_f32 v55, v70, v71
	global_store_dwordx4 v[66:67], v[48:51], off
	global_store_dwordx4 v[64:65], v[52:55], off offset:256
	s_nop 0
	v_lshl_add_u64 v[48:49], v[146:147], 0, s[10:11]
	s_nop 1
	s_waitcnt vmcnt(12)
	v_mov_b32_e32 v50, v213
	v_fmamk_f32 v50, v50, 0x3a800000, v158
	v_mul_f32_e32 v51, 0x4b800000, v50
	v_cmp_gt_f32_e32 vcc, s50, v50
	s_nop 1
	v_cndmask_b32_e32 v50, v50, v51, vcc
	v_rsq_f32_e32 v52, v50
	v_add_co_u32_e64 v50, s[0:1], s56, v146
	v_mul_f32_e32 v53, 0x45800000, v52
	v_cndmask_b32_e32 v52, v52, v53, vcc
	v_pk_mul_f32 v[46:47], v[46:47], v[52:53] op_sel_hi:[1,0]
	v_pk_mul_f32 v[44:45], v[44:45], v[52:53] op_sel_hi:[1,0]
	v_pk_mul_f32 v[42:43], v[42:43], v[52:53] op_sel_hi:[1,0]
	v_pk_mul_f32 v[40:41], v[40:41], v[52:53] op_sel_hi:[1,0]
	v_pk_mul_f32 v[38:39], v[38:39], v[52:53] op_sel_hi:[1,0]
	v_pk_mul_f32 v[36:37], v[36:37], v[52:53] op_sel_hi:[1,0]
	v_pk_mul_f32 v[34:35], v[34:35], v[52:53] op_sel_hi:[1,0]
	v_pk_mul_f32 v[32:33], v[32:33], v[52:53] op_sel_hi:[1,0]
	v_max_f32_e32 v44, 0, v44
	v_max_f32_e32 v40, 0, v40
	v_max_f32_e32 v45, 0, v45
	v_max_f32_e32 v41, 0, v41
	v_max_f32_e32 v46, 0, v46
	v_max_f32_e32 v42, 0, v42
	v_max_f32_e32 v47, 0, v47
	v_max_f32_e32 v43, 0, v43
	v_max_f32_e32 v36, 0, v36
	v_max_f32_e32 v32, 0, v32
	v_max_f32_e32 v37, 0, v37
	v_max_f32_e32 v33, 0, v33
	v_max_f32_e32 v38, 0, v38
	v_max_f32_e32 v34, 0, v34
	v_max_f32_e32 v39, 0, v39
	v_max_f32_e32 v35, 0, v35
	v_pk_mul_f32 v[44:45], v[44:45], v[44:45]
	v_pk_mul_f32 v[40:41], v[40:41], v[40:41]
	v_pk_mul_f32 v[46:47], v[46:47], v[46:47]
	v_pk_mul_f32 v[42:43], v[42:43], v[42:43]
	v_addc_co_u32_e64 v51, s[0:1], 0, v147, s[0:1]
	v_pk_mul_f32 v[36:37], v[36:37], v[36:37]
	v_pk_mul_f32 v[52:53], v[32:33], v[32:33]
	v_pk_mul_f32 v[38:39], v[38:39], v[38:39]
	v_pk_mul_f32 v[54:55], v[34:35], v[34:35]
	v_cvt_pk_bf16_f32 v32, v44, v45
	v_cvt_pk_bf16_f32 v33, v46, v47
	v_cvt_pk_bf16_f32 v34, v40, v41
	v_cvt_pk_bf16_f32 v35, v42, v43
	v_cvt_pk_bf16_f32 v36, v36, v37
	v_cvt_pk_bf16_f32 v37, v38, v39
	v_cvt_pk_bf16_f32 v38, v52, v53
	v_cvt_pk_bf16_f32 v39, v54, v55
	global_store_dwordx4 v[50:51], v[32:35], off
	global_store_dwordx4 v[48:49], v[36:39], off offset:256
	s_nop 0
	v_lshl_add_u64 v[32:33], v[146:147], 0, s[12:13]
	s_nop 1
	s_waitcnt vmcnt(13)
; DI unsigned pk2(float a, float b) { f32x2 v = {a, b}; hbf2 r = __builtin_convertvector(v, hbf2); return __builtin_bit_cast(unsigned, r); }
; #define PG8_WAIT_V(n) asm volatile("s_waitcnt vmcnt(" #n ")" ::: "memory")
; #define PG8_BAR __builtin_amdgcn_s_barrier()
; template <class Epi>
; __device__ __forceinline__ void gemm_phase(LAS unsigned char* lds, const Gemm g, const StaticOrder& S, const Epi& E) {
;     ...
;     PG8_WAIT_V(0);
;     if (wr == 0) PG8_BAR;
;     PG8_BAR;
;     DI void operator()(const f32x4 (&acc)[2][2][4][2], const Unit& u, int wr, int wc, int fr, int fq) const {
;     ...
; #pragma unroll
;         for (int ai = 0; ai < 2; ++ai)
; #pragma unroll
;             for (int m = 0; m < 4; ++m) {
;                 const int r = row0 + ai * 128 + m * 16;
;                 const float rstd = rsqrtf(ss[r] * (1.0f / 1024.0f) + EPS);
;                 bf16_t* rowp = HID + (size_t)r * 4096 + col0;
; #pragma unroll
;                 for (int bj = 0; bj < 2; ++bj) {
;                     f32x4 v0 = acc[ai][bj][m][0] * rstd, v1 = acc[ai][bj][m][1] * rstd;
; #pragma unroll
;                     for (int j = 0; j < 4; ++j) { float a = fmaxf(v0[j], 0.f), b = fmaxf(v1[j], 0.f); v0[j] = a * a; v1[j] = b * b; }
;                     u32x4 w; w.x = pk2(v0[0], v0[1]); w.y = pk2(v0[2], v0[3]); w.z = pk2(v1[0], v1[1]); w.w = pk2(v1[2], v1[3]);
;                     *(u32x4*)(rowp + bj * 128) = w;
;                 }
	v_mov_b32_e32 v34, v214
	v_fmamk_f32 v34, v34, 0x3a800000, v158
	v_mul_f32_e32 v35, 0x4b800000, v34
	v_cmp_gt_f32_e32 vcc, s50, v34
	s_nop 1
	v_cndmask_b32_e32 v34, v34, v35, vcc
	v_rsq_f32_e32 v36, v34
	v_add_co_u32_e64 v34, s[0:1], s57, v146
	v_mul_f32_e32 v37, 0x45800000, v36
	v_cndmask_b32_e32 v36, v36, v37, vcc
	v_pk_mul_f32 v[30:31], v[30:31], v[36:37] op_sel_hi:[1,0]
	v_pk_mul_f32 v[28:29], v[28:29], v[36:37] op_sel_hi:[1,0]
	v_pk_mul_f32 v[26:27], v[26:27], v[36:37] op_sel_hi:[1,0]
	v_pk_mul_f32 v[24:25], v[24:25], v[36:37] op_sel_hi:[1,0]
	v_pk_mul_f32 v[22:23], v[22:23], v[36:37] op_sel_hi:[1,0]
	v_pk_mul_f32 v[20:21], v[20:21], v[36:37] op_sel_hi:[1,0]
	v_pk_mul_f32 v[18:19], v[18:19], v[36:37] op_sel_hi:[1,0]
	v_pk_mul_f32 v[16:17], v[16:17], v[36:37] op_sel_hi:[1,0]
	v_max_f32_e32 v28, 0, v28
	v_max_f32_e32 v24, 0, v24
	v_max_f32_e32 v29, 0, v29
	v_max_f32_e32 v25, 0, v25
	v_max_f32_e32 v30, 0, v30
	v_max_f32_e32 v26, 0, v26
	v_max_f32_e32 v31, 0, v31
	v_max_f32_e32 v27, 0, v27
	v_max_f32_e32 v20, 0, v20
	v_max_f32_e32 v16, 0, v16
	v_max_f32_e32 v21, 0, v21
	v_max_f32_e32 v17, 0, v17
	v_max_f32_e32 v22, 0, v22
	v_max_f32_e32 v18, 0, v18
	v_max_f32_e32 v23, 0, v23
	v_max_f32_e32 v19, 0, v19
	v_pk_mul_f32 v[28:29], v[28:29], v[28:29]
	v_pk_mul_f32 v[24:25], v[24:25], v[24:25]
	v_pk_mul_f32 v[30:31], v[30:31], v[30:31]
	v_pk_mul_f32 v[26:27], v[26:27], v[26:27]
	v_addc_co_u32_e64 v35, s[0:1], 0, v147, s[0:1]
	v_pk_mul_f32 v[20:21], v[20:21], v[20:21]
	v_pk_mul_f32 v[36:37], v[16:17], v[16:17]
	v_pk_mul_f32 v[22:23], v[22:23], v[22:23]
	v_pk_mul_f32 v[38:39], v[18:19], v[18:19]
	v_cvt_pk_bf16_f32 v16, v28, v29
	v_cvt_pk_bf16_f32 v17, v30, v31
	v_cvt_pk_bf16_f32 v18, v24, v25
	v_cvt_pk_bf16_f32 v19, v26, v27
	v_cvt_pk_bf16_f32 v20, v20, v21
	v_cvt_pk_bf16_f32 v21, v22, v23
	v_cvt_pk_bf16_f32 v22, v36, v37
	v_cvt_pk_bf16_f32 v23, v38, v39
	global_store_dwordx4 v[34:35], v[16:19], off
	global_store_dwordx4 v[32:33], v[20:23], off offset:256
	s_nop 0
	s_and_b64 vcc, exec, s[4:5]
	v_lshl_add_u64 v[16:17], v[146:147], 0, s[14:15]
	s_nop 1
	s_waitcnt vmcnt(14)
	v_mov_b32_e32 v18, v215
	v_fmamk_f32 v18, v18, 0x3a800000, v158
	v_mul_f32_e32 v19, 0x4b800000, v18
	v_cmp_gt_f32_e64 s[0:1], s50, v18
	s_nop 1
	v_cndmask_b32_e64 v18, v18, v19, s[0:1]
	v_rsq_f32_e32 v20, v18
	v_add_co_u32_e64 v18, s[4:5], s58, v146
	v_mul_f32_e32 v21, 0x45800000, v20
	v_cndmask_b32_e64 v20, v20, v21, s[0:1]
	v_pk_mul_f32 v[14:15], v[14:15], v[20:21] op_sel_hi:[1,0]
	v_pk_mul_f32 v[12:13], v[12:13], v[20:21] op_sel_hi:[1,0]
	v_pk_mul_f32 v[10:11], v[10:11], v[20:21] op_sel_hi:[1,0]
	v_pk_mul_f32 v[8:9], v[8:9], v[20:21] op_sel_hi:[1,0]
	v_pk_mul_f32 v[6:7], v[6:7], v[20:21] op_sel_hi:[1,0]
	v_pk_mul_f32 v[4:5], v[4:5], v[20:21] op_sel_hi:[1,0]
	v_pk_mul_f32 v[2:3], v[2:3], v[20:21] op_sel_hi:[1,0]
	v_pk_mul_f32 v[0:1], v[0:1], v[20:21] op_sel_hi:[1,0]
	v_max_f32_e32 v12, 0, v12
	v_max_f32_e32 v8, 0, v8
	v_max_f32_e32 v13, 0, v13
	v_max_f32_e32 v9, 0, v9
	v_max_f32_e32 v14, 0, v14
	v_max_f32_e32 v10, 0, v10
	v_max_f32_e32 v15, 0, v15
	v_max_f32_e32 v11, 0, v11
	v_max_f32_e32 v4, 0, v4
	v_max_f32_e32 v0, 0, v0
	v_max_f32_e32 v5, 0, v5
	v_max_f32_e32 v1, 0, v1
	v_max_f32_e32 v6, 0, v6
	v_max_f32_e32 v2, 0, v2
	v_max_f32_e32 v7, 0, v7
	v_max_f32_e32 v3, 0, v3
	v_pk_mul_f32 v[12:13], v[12:13], v[12:13]
	v_pk_mul_f32 v[8:9], v[8:9], v[8:9]
	v_pk_mul_f32 v[14:15], v[14:15], v[14:15]
	v_pk_mul_f32 v[10:11], v[10:11], v[10:11]
	v_addc_co_u32_e64 v19, s[4:5], 0, v147, s[4:5]
	v_pk_mul_f32 v[4:5], v[4:5], v[4:5]
	v_pk_mul_f32 v[20:21], v[0:1], v[0:1]
	v_pk_mul_f32 v[6:7], v[6:7], v[6:7]
	v_pk_mul_f32 v[22:23], v[2:3], v[2:3]
	v_cvt_pk_bf16_f32 v0, v12, v13
	v_cvt_pk_bf16_f32 v1, v14, v15
	v_cvt_pk_bf16_f32 v2, v8, v9
	v_cvt_pk_bf16_f32 v3, v10, v11
	v_cvt_pk_bf16_f32 v4, v4, v5
	v_cvt_pk_bf16_f32 v5, v6, v7
	v_cvt_pk_bf16_f32 v6, v20, v21
	v_cvt_pk_bf16_f32 v7, v22, v23
	global_store_dwordx4 v[18:19], v[0:3], off
	global_store_dwordx4 v[16:17], v[4:7], off offset:256
	s_cbranch_vccz .LBB0_919
	s_waitcnt vmcnt(0)
	s_cmpk_gt_u32 s2, 0xff
	s_cbranch_scc1 .LBB0_930
	s_barrier

; #define PG8_STAGE(bufoff, gbase, voff) do { _Pragma("unroll") for (int _i = 0; _i < 2; ++_i) \
;         __builtin_amdgcn_global_load_lds((const unsigned*)((const char*)(gbase) + (voff)[_i]), (LAS unsigned*)(lds + (bufoff) + ldsw + _i * 8192), 16, 0, 0); } while (0)
; #define PG8_LDA(dst, b, h) do { _Pragma("unroll") for (int m = 0; m < 4; ++m) _Pragma("unroll") for (int k = 0; k < 2; ++k) dst[m][k] = *(const LAS bf16x8*)(lds + PG8_SA(b, h) + aoff + m * 2048 + k * 1024); } while (0)
; #define PG8_LDB(dst, b, h) do { _Pragma("unroll") for (int n = 0; n < 2; ++n) _Pragma("unroll") for (int k = 0; k < 2; ++k) dst[n][k] = *(const LAS bf16x8*)(lds + PG8_SB(b, h) + boff + n * 2048 + k * 1024); } while (0)
; #define PG8_WAIT_V(n) asm volatile("s_waitcnt vmcnt(" #n ")" ::: "memory")
; #define PG8_WAIT_L(n) asm volatile("s_waitcnt lgkmcnt(" #n ")" ::: "memory")
; #define PG8_BAR __builtin_amdgcn_s_barrier()
; #define PG8_SCHED __builtin_amdgcn_sched_barrier(0)
; template <class Epi>
; __device__ __forceinline__ void gemm_phase(LAS unsigned char* lds, const Gemm g, const StaticOrder& S, const Epi& E) {
;     ...
;             PG8_LDB(B0, 0, 0); PG8_SCHED; PG8_LDA(At, 0, 0); PG8_STAGE(PG8_SA(1, 1), a1 + hstep, voffA);
;             PG8_WAIT_L(8); PG8_BAR; PG8_WAIT_L(0); PG8_MMA(0, 0, At, B0); PG8_BAR; PG8_SCHED;
;             PG8_LDB(B1, 0, 1); PG8_STAGE(PG8_SB(0, 0), b2, voffB);
;             PG8_BAR; PG8_WAIT_L(0); PG8_MMA(0, 1, At, B1); PG8_BAR;
;             PG8_LDA(At, 0, 1); PG8_STAGE(PG8_SA(0, 0), a2, voffA);
;             PG8_BAR; PG8_WAIT_L(0); PG8_MMA(1, 0, At, B0); PG8_BAR; PG8_SCHED;
;             PG8_STAGE(PG8_SB(0, 1), b2 + hstep, voffB);
;             PG8_WAIT_V(6); PG8_BAR; PG8_MMA(1, 1, At, B1); PG8_BAR;
;             PG8_LDB(B0, 1, 0); PG8_SCHED; PG8_LDA(At, 1, 0); PG8_STAGE(PG8_SA(0, 1), a2 + hstep, voffA);
;             PG8_WAIT_L(8); PG8_BAR; PG8_WAIT_L(0); PG8_MMA(0, 0, At, B0); PG8_BAR; PG8_SCHED;
;             PG8_LDB(B1, 1, 1); PG8_STAGE(PG8_SB(1, 0), b3, voffB);
;             PG8_BAR; PG8_WAIT_L(0); PG8_MMA(0, 1, At, B1); PG8_BAR;
;             PG8_LDA(At, 1, 1); PG8_STAGE(PG8_SA(1, 0), a3, voffA);
;             PG8_BAR; PG8_WAIT_L(0); PG8_MMA(1, 0, At, B0); PG8_BAR; PG8_SCHED;
;             PG8_STAGE(PG8_SB(1, 1), b3 + hstep, voffB);
;             PG8_WAIT_V(6); PG8_BAR; PG8_MMA(1, 1, At, B1); PG8_BAR;
.LBB0_1464:
	ds_read_b128 v[144:147], v155
	ds_read_b128 v[148:151], v155 offset:1024
	ds_read_b128 v[160:163], v155 offset:2048
	ds_read_b128 v[164:167], v155 offset:3072
	s_add_u32 s30, s0, 0xfffc0080
	s_addc_u32 s31, s1, -1
	s_cmp_eq_u32 s70, 12
	s_cselect_b32 s37, s23, s31
	s_cselect_b32 s36, s60, s30
	s_cselect_b32 s31, s21, s63
	s_cselect_b32 s30, s61, s62
	v_lshl_add_u64 v[176:177], s[0:1], 0, v[136:137]
	s_add_i32 m0, s29, 0xc000
	ds_read_b128 v[168:171], v156
	ds_read_b128 v[172:175], v156 offset:1024
	ds_read_b128 v[180:183], v156 offset:2048
	ds_read_b128 v[184:187], v156 offset:3072
	ds_read_b128 v[188:191], v156 offset:4096
	ds_read_b128 v[192:195], v156 offset:5120
	ds_read_b128 v[196:199], v156 offset:6144
	ds_read_b128 v[200:203], v156 offset:7168
	global_load_lds_dwordx4 v[176:177], off
	v_lshl_add_u64 v[176:177], s[0:1], 0, v[138:139]
	s_add_i32 m0, s29, 0xe000
	s_nop 0
	global_load_lds_dwordx4 v[176:177], off
	s_waitcnt lgkmcnt(8)
	s_barrier
	s_waitcnt lgkmcnt(0)
	s_setprio 1
	s_waitcnt lgkmcnt(0)
	v_mfma_f32_16x16x32_bf16 v[124:127], v[144:147], v[168:171], v[124:127]
	v_mfma_f32_16x16x32_bf16 v[120:123], v[160:163], v[168:171], v[120:123]
	v_mfma_f32_16x16x32_bf16 v[108:111], v[144:147], v[180:183], v[108:111]
	v_mfma_f32_16x16x32_bf16 v[104:107], v[160:163], v[180:183], v[104:107]
	v_mfma_f32_16x16x32_bf16 v[92:95], v[144:147], v[188:191], v[92:95]
	v_mfma_f32_16x16x32_bf16 v[88:91], v[160:163], v[188:191], v[88:91]
	v_mfma_f32_16x16x32_bf16 v[76:79], v[144:147], v[196:199], v[76:79]
	v_mfma_f32_16x16x32_bf16 v[72:75], v[160:163], v[196:199], v[72:75]
	v_mfma_f32_16x16x32_bf16 v[124:127], v[148:151], v[172:175], v[124:127]
	v_mfma_f32_16x16x32_bf16 v[120:123], v[164:167], v[172:175], v[120:123]
	v_mfma_f32_16x16x32_bf16 v[108:111], v[148:151], v[184:187], v[108:111]
	v_mfma_f32_16x16x32_bf16 v[104:107], v[164:167], v[184:187], v[104:107]
	v_mfma_f32_16x16x32_bf16 v[92:95], v[148:151], v[192:195], v[92:95]
	v_mfma_f32_16x16x32_bf16 v[88:91], v[164:167], v[192:195], v[88:91]
	v_mfma_f32_16x16x32_bf16 v[76:79], v[148:151], v[200:203], v[76:79]
	v_mfma_f32_16x16x32_bf16 v[72:75], v[164:167], v[200:203], v[72:75]
	s_setprio 0
	s_barrier
	s_add_i32 s71, s48, s39
	v_lshl_add_u64 v[176:177], s[30:31], 0, v[130:131]
	s_mov_b32 m0, s71
	ds_read_b128 v[204:207], v157
	ds_read_b128 v[208:211], v157 offset:1024
	ds_read_b128 v[212:215], v157 offset:2048
	ds_read_b128 v[216:219], v157 offset:3072
	global_load_lds_dwordx4 v[176:177], off
	v_lshl_add_u64 v[220:221], s[30:31], 0, v[134:135]
	s_add_i32 m0, s71, 0x2000
	s_nop 0
	global_load_lds_dwordx4 v[220:221], off
	s_barrier
	s_waitcnt lgkmcnt(0)
	s_setprio 1
	s_waitcnt lgkmcnt(0)
	v_mfma_f32_16x16x32_bf16 v[116:119], v[204:207], v[168:171], v[116:119]
	v_mfma_f32_16x16x32_bf16 v[112:115], v[212:215], v[168:171], v[112:115]
	v_mfma_f32_16x16x32_bf16 v[100:103], v[204:207], v[180:183], v[100:103]
	v_mfma_f32_16x16x32_bf16 v[96:99], v[212:215], v[180:183], v[96:99]
	v_mfma_f32_16x16x32_bf16 v[84:87], v[204:207], v[188:191], v[84:87]
	v_mfma_f32_16x16x32_bf16 v[80:83], v[212:215], v[188:191], v[80:83]
	v_mfma_f32_16x16x32_bf16 v[68:71], v[204:207], v[196:199], v[68:71]
	v_mfma_f32_16x16x32_bf16 v[64:67], v[212:215], v[196:199], v[64:67]
	v_mfma_f32_16x16x32_bf16 v[116:119], v[208:211], v[172:175], v[116:119]
	v_mfma_f32_16x16x32_bf16 v[112:115], v[216:219], v[172:175], v[112:115]
	v_mfma_f32_16x16x32_bf16 v[100:103], v[208:211], v[184:187], v[100:103]
	v_mfma_f32_16x16x32_bf16 v[96:99], v[216:219], v[184:187], v[96:99]
	v_mfma_f32_16x16x32_bf16 v[84:87], v[208:211], v[192:195], v[84:87]
	v_mfma_f32_16x16x32_bf16 v[80:83], v[216:219], v[192:195], v[80:83]
	v_mfma_f32_16x16x32_bf16 v[68:71], v[208:211], v[200:203], v[68:71]
	v_mfma_f32_16x16x32_bf16 v[64:67], v[216:219], v[200:203], v[64:67]
	s_setprio 0
	s_mov_b32 m0, s29
	v_lshl_add_u64 v[222:223], s[36:37], 0, v[128:129]
	s_barrier
	ds_read_b128 v[168:171], v156 offset:16384
	ds_read_b128 v[172:175], v156 offset:17408
	ds_read_b128 v[180:183], v156 offset:18432
	ds_read_b128 v[184:187], v156 offset:19456
	ds_read_b128 v[188:191], v156 offset:20480
	ds_read_b128 v[192:195], v156 offset:21504
	ds_read_b128 v[196:199], v156 offset:22528
	ds_read_b128 v[200:203], v156 offset:23552
	global_load_lds_dwordx4 v[222:223], off
	v_lshl_add_u64 v[224:225], s[36:37], 0, v[132:133]
	s_mov_b32 m0, s40
	s_nop 0
	global_load_lds_dwordx4 v[224:225], off
	s_barrier
	s_waitcnt lgkmcnt(0)
	s_setprio 1
	s_waitcnt lgkmcnt(0)
	v_mfma_f32_16x16x32_bf16 v[60:63], v[144:147], v[168:171], v[60:63]
	v_mfma_f32_16x16x32_bf16 v[56:59], v[160:163], v[168:171], v[56:59]
	v_mfma_f32_16x16x32_bf16 v[44:47], v[144:147], v[180:183], v[44:47]
	v_mfma_f32_16x16x32_bf16 v[40:43], v[160:163], v[180:183], v[40:43]
	v_mfma_f32_16x16x32_bf16 v[28:31], v[144:147], v[188:191], v[28:31]
	v_mfma_f32_16x16x32_bf16 v[24:27], v[160:163], v[188:191], v[24:27]
	v_mfma_f32_16x16x32_bf16 v[12:15], v[144:147], v[196:199], v[12:15]
	v_mfma_f32_16x16x32_bf16 v[8:11], v[160:163], v[196:199], v[8:11]
	v_mfma_f32_16x16x32_bf16 v[60:63], v[148:151], v[172:175], v[60:63]
	v_mfma_f32_16x16x32_bf16 v[56:59], v[164:167], v[172:175], v[56:59]
	v_mfma_f32_16x16x32_bf16 v[44:47], v[148:151], v[184:187], v[44:47]
	v_mfma_f32_16x16x32_bf16 v[40:43], v[164:167], v[184:187], v[40:43]
	v_mfma_f32_16x16x32_bf16 v[28:31], v[148:151], v[192:195], v[28:31]
	v_mfma_f32_16x16x32_bf16 v[24:27], v[164:167], v[192:195], v[24:27]
	v_mfma_f32_16x16x32_bf16 v[12:15], v[148:151], v[200:203], v[12:15]
	v_mfma_f32_16x16x32_bf16 v[8:11], v[164:167], v[200:203], v[8:11]
	s_setprio 0
	s_barrier
; #define PG8_STAGE(bufoff, gbase, voff) do { _Pragma("unroll") for (int _i = 0; _i < 2; ++_i) \
;         __builtin_amdgcn_global_load_lds((const unsigned*)((const char*)(gbase) + (voff)[_i]), (LAS unsigned*)(lds + (bufoff) + ldsw + _i * 8192), 16, 0, 0); } while (0)
; #define PG8_LDA(dst, b, h) do { _Pragma("unroll") for (int m = 0; m < 4; ++m) _Pragma("unroll") for (int k = 0; k < 2; ++k) dst[m][k] = *(const LAS bf16x8*)(lds + PG8_SA(b, h) + aoff + m * 2048 + k * 1024); } while (0)
; #define PG8_LDB(dst, b, h) do { _Pragma("unroll") for (int n = 0; n < 2; ++n) _Pragma("unroll") for (int k = 0; k < 2; ++k) dst[n][k] = *(const LAS bf16x8*)(lds + PG8_SB(b, h) + boff + n * 2048 + k * 1024); } while (0)
; #define PG8_WAIT_V(n) asm volatile("s_waitcnt vmcnt(" #n ")" ::: "memory")
; #define PG8_WAIT_L(n) asm volatile("s_waitcnt lgkmcnt(" #n ")" ::: "memory")
; #define PG8_BAR __builtin_amdgcn_s_barrier()
; #define PG8_SCHED __builtin_amdgcn_sched_barrier(0)
; template <class Epi>
; __device__ __forceinline__ void gemm_phase(LAS unsigned char* lds, const Gemm g, const StaticOrder& S, const Epi& E) {
;     ...
;             PG8_LDB(B0, 0, 0); PG8_SCHED; PG8_LDA(At, 0, 0); PG8_STAGE(PG8_SA(1, 1), a1 + hstep, voffA);
;             PG8_WAIT_L(8); PG8_BAR; PG8_WAIT_L(0); PG8_MMA(0, 0, At, B0); PG8_BAR; PG8_SCHED;
;             PG8_LDB(B1, 0, 1); PG8_STAGE(PG8_SB(0, 0), b2, voffB);
;             PG8_BAR; PG8_WAIT_L(0); PG8_MMA(0, 1, At, B1); PG8_BAR;
;             PG8_LDA(At, 0, 1); PG8_STAGE(PG8_SA(0, 0), a2, voffA);
;             PG8_BAR; PG8_WAIT_L(0); PG8_MMA(1, 0, At, B0); PG8_BAR; PG8_SCHED;
;             PG8_STAGE(PG8_SB(0, 1), b2 + hstep, voffB);
;             PG8_WAIT_V(6); PG8_BAR; PG8_MMA(1, 1, At, B1); PG8_BAR;
;             PG8_LDB(B0, 1, 0); PG8_SCHED; PG8_LDA(At, 1, 0); PG8_STAGE(PG8_SA(0, 1), a2 + hstep, voffA);
;             PG8_WAIT_L(8); PG8_BAR; PG8_WAIT_L(0); PG8_MMA(0, 0, At, B0); PG8_BAR; PG8_SCHED;
;             PG8_LDB(B1, 1, 1); PG8_STAGE(PG8_SB(1, 0), b3, voffB);
;             PG8_BAR; PG8_WAIT_L(0); PG8_MMA(0, 1, At, B1); PG8_BAR;
;             PG8_LDA(At, 1, 1); PG8_STAGE(PG8_SA(1, 0), a3, voffA);
;             PG8_BAR; PG8_WAIT_L(0); PG8_MMA(1, 0, At, B0); PG8_BAR; PG8_SCHED;
;             PG8_STAGE(PG8_SB(1, 1), b3 + hstep, voffB);
;             PG8_WAIT_V(6); PG8_BAR; PG8_MMA(1, 1, At, B1); PG8_BAR;
	s_add_u32 s72, s30, 0x40000
	s_addc_u32 s73, s31, 0
	s_add_i32 s71, s49, s39
	v_lshl_add_u64 v[144:145], s[72:73], 0, v[130:131]
	s_mov_b32 m0, s71
	s_nop 0
	global_load_lds_dwordx4 v[144:145], off
	v_lshl_add_u64 v[144:145], s[72:73], 0, v[134:135]
	s_add_i32 m0, s71, 0x2000
	s_nop 0
	global_load_lds_dwordx4 v[144:145], off
	s_waitcnt vmcnt(6)
	s_barrier
	s_setprio 1
	v_mfma_f32_16x16x32_bf16 v[52:55], v[204:207], v[168:171], v[52:55]
	v_mfma_f32_16x16x32_bf16 v[48:51], v[212:215], v[168:171], v[48:51]
	v_mfma_f32_16x16x32_bf16 v[36:39], v[204:207], v[180:183], v[36:39]
	v_mfma_f32_16x16x32_bf16 v[32:35], v[212:215], v[180:183], v[32:35]
	v_mfma_f32_16x16x32_bf16 v[20:23], v[204:207], v[188:191], v[20:23]
	v_mfma_f32_16x16x32_bf16 v[16:19], v[212:215], v[188:191], v[16:19]
	v_mfma_f32_16x16x32_bf16 v[4:7], v[204:207], v[196:199], v[4:7]
	v_mfma_f32_16x16x32_bf16 v[0:3], v[212:215], v[196:199], v[0:3]
	v_mfma_f32_16x16x32_bf16 v[52:55], v[208:211], v[172:175], v[52:55]
	v_mfma_f32_16x16x32_bf16 v[48:51], v[216:219], v[172:175], v[48:51]
	v_mfma_f32_16x16x32_bf16 v[36:39], v[208:211], v[184:187], v[36:39]
	v_mfma_f32_16x16x32_bf16 v[32:35], v[216:219], v[184:187], v[32:35]
	v_mfma_f32_16x16x32_bf16 v[20:23], v[208:211], v[192:195], v[20:23]
	v_mfma_f32_16x16x32_bf16 v[16:19], v[216:219], v[192:195], v[16:19]
	v_mfma_f32_16x16x32_bf16 v[4:7], v[208:211], v[200:203], v[4:7]
	v_mfma_f32_16x16x32_bf16 v[0:3], v[216:219], v[200:203], v[0:3]
	s_setprio 0
	s_add_i32 s71, 0, 0x18000
	v_add_u32_e32 v159, s71, v153
	s_barrier
	ds_read_b128 v[144:147], v159
	ds_read_b128 v[148:151], v159 offset:1024
	ds_read_b128 v[160:163], v159 offset:2048
	ds_read_b128 v[164:167], v159 offset:3072
	s_add_u32 s36, s36, 0x40000
	s_addc_u32 s37, s37, 0
	s_mov_b32 m0, s41
	v_lshl_add_u64 v[204:205], s[36:37], 0, v[128:129]
	ds_read_b128 v[168:171], v156 offset:32768
	ds_read_b128 v[172:175], v156 offset:33792
	ds_read_b128 v[180:183], v156 offset:34816
	ds_read_b128 v[184:187], v156 offset:35840
	ds_read_b128 v[188:191], v156 offset:36864
	ds_read_b128 v[192:195], v156 offset:37888
	ds_read_b128 v[196:199], v156 offset:38912
	ds_read_b128 v[200:203], v156 offset:39936
	global_load_lds_dwordx4 v[204:205], off
	v_lshl_add_u64 v[204:205], s[36:37], 0, v[132:133]
	s_mov_b32 m0, s42
	s_nop 0
	global_load_lds_dwordx4 v[204:205], off
	s_waitcnt lgkmcnt(8)
	s_barrier
	s_waitcnt lgkmcnt(0)
	s_setprio 1
	s_waitcnt lgkmcnt(0)
	v_mfma_f32_16x16x32_bf16 v[124:127], v[144:147], v[168:171], v[124:127]
	v_mfma_f32_16x16x32_bf16 v[120:123], v[160:163], v[168:171], v[120:123]
	v_mfma_f32_16x16x32_bf16 v[108:111], v[144:147], v[180:183], v[108:111]
	v_mfma_f32_16x16x32_bf16 v[104:107], v[160:163], v[180:183], v[104:107]
	v_mfma_f32_16x16x32_bf16 v[92:95], v[144:147], v[188:191], v[92:95]
	v_mfma_f32_16x16x32_bf16 v[88:91], v[160:163], v[188:191], v[88:91]
	v_mfma_f32_16x16x32_bf16 v[76:79], v[144:147], v[196:199], v[76:79]
	v_mfma_f32_16x16x32_bf16 v[72:75], v[160:163], v[196:199], v[72:75]
	v_mfma_f32_16x16x32_bf16 v[124:127], v[148:151], v[172:175], v[124:127]
	v_mfma_f32_16x16x32_bf16 v[120:123], v[164:167], v[172:175], v[120:123]
	v_mfma_f32_16x16x32_bf16 v[108:111], v[148:151], v[184:187], v[108:111]
	v_mfma_f32_16x16x32_bf16 v[104:107], v[164:167], v[184:187], v[104:107]
	v_mfma_f32_16x16x32_bf16 v[92:95], v[148:151], v[192:195], v[92:95]
	v_mfma_f32_16x16x32_bf16 v[88:91], v[164:167], v[192:195], v[88:91]
	v_mfma_f32_16x16x32_bf16 v[76:79], v[148:151], v[200:203], v[76:79]
	v_mfma_f32_16x16x32_bf16 v[72:75], v[164:167], v[200:203], v[72:75]
	s_setprio 0
	s_barrier
	s_add_i32 s36, 0, 0x1c000
	s_add_i32 s37, s71, s39
	v_add_u32_e32 v159, s36, v153
	v_lshl_add_u64 v[176:177], v[176:177], 0, s[6:7]
	s_mov_b32 m0, s37
	ds_read_b128 v[204:207], v159
	ds_read_b128 v[208:211], v159 offset:1024
	ds_read_b128 v[212:215], v159 offset:2048
	ds_read_b128 v[216:219], v159 offset:3072
	global_load_lds_dwordx4 v[176:177], off
	v_lshl_add_u64 v[176:177], v[220:221], 0, s[6:7]
	s_add_i32 m0, s37, 0x2000
	s_nop 0
	global_load_lds_dwordx4 v[176:177], off
	s_barrier
	s_waitcnt lgkmcnt(0)
	s_setprio 1
	s_waitcnt lgkmcnt(0)
	v_mfma_f32_16x16x32_bf16 v[116:119], v[204:207], v[168:171], v[116:119]
	v_mfma_f32_16x16x32_bf16 v[112:115], v[212:215], v[168:171], v[112:115]
	v_mfma_f32_16x16x32_bf16 v[100:103], v[204:207], v[180:183], v[100:103]
	v_mfma_f32_16x16x32_bf16 v[96:99], v[212:215], v[180:183], v[96:99]
	v_mfma_f32_16x16x32_bf16 v[84:87], v[204:207], v[188:191], v[84:87]
	v_mfma_f32_16x16x32_bf16 v[80:83], v[212:215], v[188:191], v[80:83]
	v_mfma_f32_16x16x32_bf16 v[68:71], v[204:207], v[196:199], v[68:71]
	v_mfma_f32_16x16x32_bf16 v[64:67], v[212:215], v[196:199], v[64:67]
	v_mfma_f32_16x16x32_bf16 v[116:119], v[208:211], v[172:175], v[116:119]
	v_mfma_f32_16x16x32_bf16 v[112:115], v[216:219], v[172:175], v[112:115]
	v_mfma_f32_16x16x32_bf16 v[100:103], v[208:211], v[184:187], v[100:103]
	v_mfma_f32_16x16x32_bf16 v[96:99], v[216:219], v[184:187], v[96:99]
	v_mfma_f32_16x16x32_bf16 v[84:87], v[208:211], v[192:195], v[84:87]
	v_mfma_f32_16x16x32_bf16 v[80:83], v[216:219], v[192:195], v[80:83]
	v_mfma_f32_16x16x32_bf16 v[68:71], v[208:211], v[200:203], v[68:71]
	v_mfma_f32_16x16x32_bf16 v[64:67], v[216:219], v[200:203], v[64:67]
	s_setprio 0
	s_mov_b32 m0, s44
	v_lshl_add_u64 v[176:177], v[222:223], 0, s[6:7]
	s_barrier
	ds_read_b128 v[168:171], v156 offset:49152
	ds_read_b128 v[172:175], v156 offset:50176
	ds_read_b128 v[180:183], v156 offset:51200
	ds_read_b128 v[184:187], v156 offset:52224
	ds_read_b128 v[188:191], v156 offset:53248
	ds_read_b128 v[192:195], v156 offset:54272
	ds_read_b128 v[196:199], v156 offset:55296
	ds_read_b128 v[200:203], v156 offset:56320
	global_load_lds_dwordx4 v[176:177], off
	v_lshl_add_u64 v[176:177], v[224:225], 0, s[6:7]
	s_mov_b32 m0, s45
	s_nop 0
	global_load_lds_dwordx4 v[176:177], off
	s_barrier
; DI unsigned pk2(float a, float b) { f32x2 v = {a, b}; hbf2 r = __builtin_convertvector(v, hbf2); return __builtin_bit_cast(unsigned, r); }
; #define PG8_STAGE(bufoff, gbase, voff) do { _Pragma("unroll") for (int _i = 0; _i < 2; ++_i) \
;         __builtin_amdgcn_global_load_lds((const unsigned*)((const char*)(gbase) + (voff)[_i]), (LAS unsigned*)(lds + (bufoff) + ldsw + _i * 8192), 16, 0, 0); } while (0)
; #define PG8_WAIT_V(n) asm volatile("s_waitcnt vmcnt(" #n ")" ::: "memory")
; #define PG8_WAIT_L(n) asm volatile("s_waitcnt lgkmcnt(" #n ")" ::: "memory")
; #define PG8_BAR __builtin_amdgcn_s_barrier()
; template <class Epi>
; __device__ __forceinline__ void gemm_phase(LAS unsigned char* lds, const Gemm g, const StaticOrder& S, const Epi& E) {
;     ...
;             PG8_WAIT_V(6); PG8_BAR; PG8_MMA(1, 1, At, B1); PG8_BAR;
;             PG8_LDB(B0, 1, 0); PG8_SCHED; PG8_LDA(At, 1, 0); PG8_STAGE(PG8_SA(0, 1), a2 + hstep, voffA);
;             PG8_WAIT_L(8); PG8_BAR; PG8_WAIT_L(0); PG8_MMA(0, 0, At, B0); PG8_BAR; PG8_SCHED;
;             PG8_LDB(B1, 1, 1); PG8_STAGE(PG8_SB(1, 0), b3, voffB);
;             PG8_BAR; PG8_WAIT_L(0); PG8_MMA(0, 1, At, B1); PG8_BAR;
;             PG8_LDA(At, 1, 1); PG8_STAGE(PG8_SA(1, 0), a3, voffA);
;             PG8_BAR; PG8_WAIT_L(0); PG8_MMA(1, 0, At, B0); PG8_BAR; PG8_SCHED;
;             PG8_STAGE(PG8_SB(1, 1), b3 + hstep, voffB);
;             PG8_WAIT_V(6); PG8_BAR; PG8_MMA(1, 1, At, B1); PG8_BAR;
;     DI void operator()(const f32x4 (&acc)[2][2][4][2], const Unit& u, int wr, int wc, int fr, int fq) const {
;     ...
; #pragma unroll
;         for (int ai = 0; ai < 2; ++ai)
; #pragma unroll
;             for (int m = 0; m < 4; ++m) {
;                 const int r = row0 + ai * 128 + m * 16;
;                 const float rstd = rsqrtf(ss[r] * (1.0f / 1024.0f) + EPS);
;                 bf16_t* rowp = HID + (size_t)r * 4096 + col0;
; #pragma unroll
;                 for (int bj = 0; bj < 2; ++bj) {
;                     f32x4 v0 = acc[ai][bj][m][0] * rstd, v1 = acc[ai][bj][m][1] * rstd;
; #pragma unroll
;                     for (int j = 0; j < 4; ++j) { float a = fmaxf(v0[j], 0.f), b = fmaxf(v1[j], 0.f); v0[j] = a * a; v1[j] = b * b; }
;                     u32x4 w; w.x = pk2(v0[0], v0[1]); w.y = pk2(v0[2], v0[3]); w.z = pk2(v1[0], v1[1]); w.w = pk2(v1[2], v1[3]);
;                     *(u32x4*)(rowp + bj * 128) = w;
;                 }
	s_waitcnt lgkmcnt(0)
	s_setprio 1
	s_waitcnt lgkmcnt(0)
	v_mfma_f32_16x16x32_bf16 v[60:63], v[144:147], v[168:171], v[60:63]
	v_mfma_f32_16x16x32_bf16 v[56:59], v[160:163], v[168:171], v[56:59]
	v_mfma_f32_16x16x32_bf16 v[44:47], v[144:147], v[180:183], v[44:47]
	v_mfma_f32_16x16x32_bf16 v[40:43], v[160:163], v[180:183], v[40:43]
	v_mfma_f32_16x16x32_bf16 v[28:31], v[144:147], v[188:191], v[28:31]
	v_mfma_f32_16x16x32_bf16 v[24:27], v[160:163], v[188:191], v[24:27]
	v_mfma_f32_16x16x32_bf16 v[12:15], v[144:147], v[196:199], v[12:15]
	v_mfma_f32_16x16x32_bf16 v[8:11], v[160:163], v[196:199], v[8:11]
	v_mfma_f32_16x16x32_bf16 v[60:63], v[148:151], v[172:175], v[60:63]
	v_mfma_f32_16x16x32_bf16 v[56:59], v[164:167], v[172:175], v[56:59]
	v_mfma_f32_16x16x32_bf16 v[44:47], v[148:151], v[184:187], v[44:47]
	v_mfma_f32_16x16x32_bf16 v[40:43], v[164:167], v[184:187], v[40:43]
	v_mfma_f32_16x16x32_bf16 v[28:31], v[148:151], v[192:195], v[28:31]
	v_mfma_f32_16x16x32_bf16 v[24:27], v[164:167], v[192:195], v[24:27]
	v_mfma_f32_16x16x32_bf16 v[12:15], v[148:151], v[200:203], v[12:15]
	v_mfma_f32_16x16x32_bf16 v[8:11], v[164:167], v[200:203], v[8:11]
	s_setprio 0
	s_barrier
	s_add_u32 s30, s30, 0x40080
	s_addc_u32 s31, s31, 0
	s_add_i32 s36, s36, s39
	v_lshl_add_u64 v[144:145], s[30:31], 0, v[130:131]
	s_mov_b32 m0, s36
	s_nop 0
	global_load_lds_dwordx4 v[144:145], off
	v_lshl_add_u64 v[144:145], s[30:31], 0, v[134:135]
	s_add_i32 m0, s36, 0x2000
	s_nop 0
	global_load_lds_dwordx4 v[144:145], off
	s_waitcnt vmcnt(6)
	s_barrier
	s_setprio 1
	v_mfma_f32_16x16x32_bf16 v[52:55], v[204:207], v[168:171], v[52:55]
	v_mfma_f32_16x16x32_bf16 v[48:51], v[212:215], v[168:171], v[48:51]
	v_mfma_f32_16x16x32_bf16 v[36:39], v[204:207], v[180:183], v[36:39]
	v_mfma_f32_16x16x32_bf16 v[32:35], v[212:215], v[180:183], v[32:35]
	v_mfma_f32_16x16x32_bf16 v[20:23], v[204:207], v[188:191], v[20:23]
	v_mfma_f32_16x16x32_bf16 v[16:19], v[212:215], v[188:191], v[16:19]
	v_mfma_f32_16x16x32_bf16 v[4:7], v[204:207], v[196:199], v[4:7]
	v_mfma_f32_16x16x32_bf16 v[0:3], v[212:215], v[196:199], v[0:3]
	v_mfma_f32_16x16x32_bf16 v[52:55], v[208:211], v[172:175], v[52:55]
	v_mfma_f32_16x16x32_bf16 v[48:51], v[216:219], v[172:175], v[48:51]
	v_mfma_f32_16x16x32_bf16 v[36:39], v[208:211], v[184:187], v[36:39]
	v_mfma_f32_16x16x32_bf16 v[32:35], v[216:219], v[184:187], v[32:35]
	v_mfma_f32_16x16x32_bf16 v[20:23], v[208:211], v[192:195], v[20:23]
	v_mfma_f32_16x16x32_bf16 v[16:19], v[216:219], v[192:195], v[16:19]
	v_mfma_f32_16x16x32_bf16 v[4:7], v[208:211], v[200:203], v[4:7]
	v_mfma_f32_16x16x32_bf16 v[0:3], v[216:219], v[200:203], v[0:3]
	s_setprio 0
	s_add_i32 s70, s70, 2
	s_add_u32 s0, s0, 0x100
	s_addc_u32 s1, s1, 0
	s_add_u32 s62, s62, 0x100
	s_addc_u32 s63, s63, 0
	s_cmp_gt_u32 s70, 13
	s_barrier
	s_cbranch_scc0 .LBB0_1464
	v_lshl_add_u32 v148, s28, 8, v152
	v_ashrrev_i32_e32 v149, 31, v148
	v_lshl_add_u64 v[144:145], v[148:149], 2, s[10:11]
	global_load_dword v159, v[144:145], off
	global_load_dword v209, v[144:145], off offset:64
	global_load_dword v210, v[144:145], off offset:128
	global_load_dword v211, v[144:145], off offset:192
	global_load_dword v212, v[144:145], off offset:512
	global_load_dword v213, v[144:145], off offset:576
	global_load_dword v214, v[144:145], off offset:640
	global_load_dword v215, v[144:145], off offset:704
	v_lshl_or_b32 v146, s59, 8, v154
	v_ashrrev_i32_e32 v147, 31, v146
	v_lshlrev_b64 v[150:151], 1, v[146:147]
	v_lshlrev_b64 v[162:163], 13, v[148:149]
	v_or_b32_e32 v160, 16, v148
	v_ashrrev_i32_e32 v161, 31, v160
	s_mov_b32 s59, s20
	s_mov_b32 s28, s22
	s_mov_b64 s[30:31], s[26:27]
	s_mov_b64 s[36:37], s[24:25]
	s_waitcnt vmcnt(7)
	v_fmamk_f32 v146, v159, 0x3a800000, v158
	v_mul_f32_e32 v147, 0x4b800000, v146
	v_cmp_gt_f32_e32 vcc, s50, v146
	s_nop 1
	v_cndmask_b32_e32 v146, v146, v147, vcc
	v_rsq_f32_e32 v149, v146
	v_lshl_add_u64 v[146:147], s[34:35], 0, v[162:163]
	v_lshl_add_u64 v[146:147], v[146:147], 0, v[150:151]
	v_lshl_add_u64 v[162:163], v[160:161], 2, s[10:11]
	v_mul_f32_e32 v159, 0x45800000, v149
	v_cndmask_b32_e32 v164, v149, v159, vcc
	v_pk_mul_f32 v[126:127], v[126:127], v[164:165] op_sel_hi:[1,0]
	v_pk_mul_f32 v[124:125], v[124:125], v[164:165] op_sel_hi:[1,0]
	v_pk_mul_f32 v[122:123], v[122:123], v[164:165] op_sel_hi:[1,0]
	v_pk_mul_f32 v[120:121], v[120:121], v[164:165] op_sel_hi:[1,0]
	v_pk_mul_f32 v[118:119], v[118:119], v[164:165] op_sel_hi:[1,0]
	v_pk_mul_f32 v[116:117], v[116:117], v[164:165] op_sel_hi:[1,0]
	v_pk_mul_f32 v[114:115], v[114:115], v[164:165] op_sel_hi:[1,0]
	v_pk_mul_f32 v[112:113], v[112:113], v[164:165] op_sel_hi:[1,0]
	v_max_f32_e32 v124, 0, v124
	v_max_f32_e32 v120, 0, v120
	v_max_f32_e32 v125, 0, v125
	v_max_f32_e32 v121, 0, v121
	v_max_f32_e32 v126, 0, v126
	v_max_f32_e32 v122, 0, v122
	v_max_f32_e32 v127, 0, v127
	v_max_f32_e32 v123, 0, v123
	v_max_f32_e32 v116, 0, v116
	v_max_f32_e32 v112, 0, v112
	v_max_f32_e32 v117, 0, v117
	v_max_f32_e32 v113, 0, v113
	v_max_f32_e32 v118, 0, v118
	v_max_f32_e32 v114, 0, v114
	v_max_f32_e32 v119, 0, v119
	v_max_f32_e32 v115, 0, v115
	v_pk_mul_f32 v[124:125], v[124:125], v[124:125]
	v_pk_mul_f32 v[120:121], v[120:121], v[120:121]
	v_pk_mul_f32 v[126:127], v[126:127], v[126:127]
	v_pk_mul_f32 v[122:123], v[122:123], v[122:123]
	v_pk_mul_f32 v[116:117], v[116:117], v[116:117]
	v_pk_mul_f32 v[164:165], v[112:113], v[112:113]
	v_pk_mul_f32 v[118:119], v[118:119], v[118:119]
	v_pk_mul_f32 v[166:167], v[114:115], v[114:115]
	v_cvt_pk_bf16_f32 v112, v124, v125
	v_cvt_pk_bf16_f32 v113, v126, v127
	v_cvt_pk_bf16_f32 v114, v120, v121
	v_cvt_pk_bf16_f32 v115, v122, v123
	v_cvt_pk_bf16_f32 v116, v116, v117
	v_cvt_pk_bf16_f32 v117, v118, v119
	v_cvt_pk_bf16_f32 v118, v164, v165
	v_cvt_pk_bf16_f32 v119, v166, v167
	global_store_dwordx4 v[146:147], v[112:115], off
	global_store_dwordx4 v[146:147], v[116:119], off offset:256
	s_nop 0
	v_lshlrev_b64 v[114:115], 13, v[160:161]
	v_or_b32_e32 v112, 32, v148
	v_lshl_add_u64 v[114:115], s[34:35], 0, v[114:115]
	v_ashrrev_i32_e32 v113, 31, v112
	v_lshl_add_u64 v[114:115], v[114:115], 0, v[150:151]
	s_nop 1
	s_waitcnt vmcnt(8)
; DI unsigned pk2(float a, float b) { f32x2 v = {a, b}; hbf2 r = __builtin_convertvector(v, hbf2); return __builtin_bit_cast(unsigned, r); }
;     DI void operator()(const f32x4 (&acc)[2][2][4][2], const Unit& u, int wr, int wc, int fr, int fq) const {
;     ...
; #pragma unroll
;         for (int ai = 0; ai < 2; ++ai)
; #pragma unroll
;             for (int m = 0; m < 4; ++m) {
;                 const int r = row0 + ai * 128 + m * 16;
;                 const float rstd = rsqrtf(ss[r] * (1.0f / 1024.0f) + EPS);
;                 bf16_t* rowp = HID + (size_t)r * 4096 + col0;
; #pragma unroll
;                 for (int bj = 0; bj < 2; ++bj) {
;                     f32x4 v0 = acc[ai][bj][m][0] * rstd, v1 = acc[ai][bj][m][1] * rstd;
; #pragma unroll
;                     for (int j = 0; j < 4; ++j) { float a = fmaxf(v0[j], 0.f), b = fmaxf(v1[j], 0.f); v0[j] = a * a; v1[j] = b * b; }
;                     u32x4 w; w.x = pk2(v0[0], v0[1]); w.y = pk2(v0[2], v0[3]); w.z = pk2(v1[0], v1[1]); w.w = pk2(v1[2], v1[3]);
;                     *(u32x4*)(rowp + bj * 128) = w;
;                 }
	v_mov_b32_e32 v116, v209
	v_fmamk_f32 v116, v116, 0x3a800000, v158
	v_mul_f32_e32 v117, 0x4b800000, v116
	v_cmp_gt_f32_e32 vcc, s50, v116
	s_nop 1
	v_cndmask_b32_e32 v116, v116, v117, vcc
	v_rsq_f32_e32 v118, v116
	v_lshl_add_u64 v[116:117], v[112:113], 2, s[10:11]
	v_mul_f32_e32 v119, 0x45800000, v118
	v_cndmask_b32_e32 v118, v118, v119, vcc
	v_pk_mul_f32 v[110:111], v[110:111], v[118:119] op_sel_hi:[1,0]
	v_pk_mul_f32 v[108:109], v[108:109], v[118:119] op_sel_hi:[1,0]
	v_pk_mul_f32 v[106:107], v[106:107], v[118:119] op_sel_hi:[1,0]
	v_pk_mul_f32 v[104:105], v[104:105], v[118:119] op_sel_hi:[1,0]
	v_pk_mul_f32 v[102:103], v[102:103], v[118:119] op_sel_hi:[1,0]
	v_pk_mul_f32 v[100:101], v[100:101], v[118:119] op_sel_hi:[1,0]
	v_pk_mul_f32 v[98:99], v[98:99], v[118:119] op_sel_hi:[1,0]
	v_pk_mul_f32 v[96:97], v[96:97], v[118:119] op_sel_hi:[1,0]
	v_max_f32_e32 v108, 0, v108
	v_max_f32_e32 v104, 0, v104
	v_max_f32_e32 v109, 0, v109
	v_max_f32_e32 v105, 0, v105
	v_max_f32_e32 v110, 0, v110
	v_max_f32_e32 v106, 0, v106
	v_max_f32_e32 v111, 0, v111
	v_max_f32_e32 v107, 0, v107
	v_max_f32_e32 v100, 0, v100
	v_max_f32_e32 v96, 0, v96
	v_max_f32_e32 v101, 0, v101
	v_max_f32_e32 v97, 0, v97
	v_max_f32_e32 v102, 0, v102
	v_max_f32_e32 v98, 0, v98
	v_max_f32_e32 v103, 0, v103
	v_max_f32_e32 v99, 0, v99
	v_pk_mul_f32 v[108:109], v[108:109], v[108:109]
	v_pk_mul_f32 v[104:105], v[104:105], v[104:105]
	v_pk_mul_f32 v[110:111], v[110:111], v[110:111]
	v_pk_mul_f32 v[106:107], v[106:107], v[106:107]
	v_pk_mul_f32 v[100:101], v[100:101], v[100:101]
	v_pk_mul_f32 v[118:119], v[96:97], v[96:97]
	v_pk_mul_f32 v[102:103], v[102:103], v[102:103]
	v_pk_mul_f32 v[120:121], v[98:99], v[98:99]
	v_cvt_pk_bf16_f32 v96, v108, v109
	v_cvt_pk_bf16_f32 v97, v110, v111
	v_cvt_pk_bf16_f32 v98, v104, v105
	v_cvt_pk_bf16_f32 v99, v106, v107
	v_cvt_pk_bf16_f32 v100, v100, v101
	v_cvt_pk_bf16_f32 v101, v102, v103
	v_cvt_pk_bf16_f32 v102, v118, v119
	v_cvt_pk_bf16_f32 v103, v120, v121
	global_store_dwordx4 v[114:115], v[96:99], off
	global_store_dwordx4 v[114:115], v[100:103], off offset:256
	s_nop 0
	v_lshlrev_b64 v[98:99], 13, v[112:113]
	v_or_b32_e32 v96, 48, v148
	v_lshl_add_u64 v[98:99], s[34:35], 0, v[98:99]
	v_ashrrev_i32_e32 v97, 31, v96
	v_lshl_add_u64 v[98:99], v[98:99], 0, v[150:151]
	s_nop 1
	s_waitcnt vmcnt(9)
	v_mov_b32_e32 v100, v210
	v_fmamk_f32 v100, v100, 0x3a800000, v158
	v_mul_f32_e32 v101, 0x4b800000, v100
	v_cmp_gt_f32_e32 vcc, s50, v100
	s_nop 1
	v_cndmask_b32_e32 v100, v100, v101, vcc
	v_rsq_f32_e32 v102, v100
	v_lshl_add_u64 v[100:101], v[96:97], 2, s[10:11]
	v_mul_f32_e32 v103, 0x45800000, v102
	v_cndmask_b32_e32 v102, v102, v103, vcc
	v_pk_mul_f32 v[94:95], v[94:95], v[102:103] op_sel_hi:[1,0]
	v_pk_mul_f32 v[92:93], v[92:93], v[102:103] op_sel_hi:[1,0]
	v_pk_mul_f32 v[90:91], v[90:91], v[102:103] op_sel_hi:[1,0]
	v_pk_mul_f32 v[88:89], v[88:89], v[102:103] op_sel_hi:[1,0]
	v_pk_mul_f32 v[86:87], v[86:87], v[102:103] op_sel_hi:[1,0]
	v_pk_mul_f32 v[84:85], v[84:85], v[102:103] op_sel_hi:[1,0]
	v_pk_mul_f32 v[82:83], v[82:83], v[102:103] op_sel_hi:[1,0]
	v_pk_mul_f32 v[80:81], v[80:81], v[102:103] op_sel_hi:[1,0]
	v_max_f32_e32 v92, 0, v92
	v_max_f32_e32 v88, 0, v88
	v_max_f32_e32 v93, 0, v93
	v_max_f32_e32 v89, 0, v89
	v_max_f32_e32 v94, 0, v94
	v_max_f32_e32 v90, 0, v90
	v_max_f32_e32 v95, 0, v95
	v_max_f32_e32 v91, 0, v91
	v_max_f32_e32 v84, 0, v84
	v_max_f32_e32 v80, 0, v80
	v_max_f32_e32 v85, 0, v85
	v_max_f32_e32 v81, 0, v81
	v_max_f32_e32 v86, 0, v86
	v_max_f32_e32 v82, 0, v82
	v_max_f32_e32 v87, 0, v87
	v_max_f32_e32 v83, 0, v83
	v_pk_mul_f32 v[92:93], v[92:93], v[92:93]
	v_pk_mul_f32 v[88:89], v[88:89], v[88:89]
	v_pk_mul_f32 v[94:95], v[94:95], v[94:95]
	v_pk_mul_f32 v[90:91], v[90:91], v[90:91]
	v_pk_mul_f32 v[84:85], v[84:85], v[84:85]
	v_pk_mul_f32 v[102:103], v[80:81], v[80:81]
	v_pk_mul_f32 v[86:87], v[86:87], v[86:87]
	v_pk_mul_f32 v[104:105], v[82:83], v[82:83]
	v_cvt_pk_bf16_f32 v80, v92, v93
	v_cvt_pk_bf16_f32 v81, v94, v95
	v_cvt_pk_bf16_f32 v82, v88, v89
	v_cvt_pk_bf16_f32 v83, v90, v91
	v_cvt_pk_bf16_f32 v84, v84, v85
	v_cvt_pk_bf16_f32 v85, v86, v87
	v_cvt_pk_bf16_f32 v86, v102, v103
	v_cvt_pk_bf16_f32 v87, v104, v105
	global_store_dwordx4 v[98:99], v[80:83], off
	global_store_dwordx4 v[98:99], v[84:87], off offset:256
	s_nop 0
	s_nop 1
	s_waitcnt vmcnt(10)
	v_mov_b32_e32 v80, v211
	v_fmamk_f32 v80, v80, 0x3a800000, v158
	v_mul_f32_e32 v81, 0x4b800000, v80
	v_cmp_gt_f32_e32 vcc, s50, v80
	s_nop 1
	v_cndmask_b32_e32 v80, v80, v81, vcc
	v_rsq_f32_e32 v82, v80
	v_lshlrev_b64 v[80:81], 13, v[96:97]
	v_lshl_add_u64 v[80:81], s[34:35], 0, v[80:81]
	v_lshl_add_u64 v[80:81], v[80:81], 0, v[150:151]
	v_mul_f32_e32 v83, 0x45800000, v82
	v_cndmask_b32_e32 v82, v82, v83, vcc
	v_pk_mul_f32 v[78:79], v[78:79], v[82:83] op_sel_hi:[1,0]
	v_pk_mul_f32 v[76:77], v[76:77], v[82:83] op_sel_hi:[1,0]
	v_pk_mul_f32 v[74:75], v[74:75], v[82:83] op_sel_hi:[1,0]
	v_pk_mul_f32 v[72:73], v[72:73], v[82:83] op_sel_hi:[1,0]
	v_pk_mul_f32 v[70:71], v[70:71], v[82:83] op_sel_hi:[1,0]
	v_pk_mul_f32 v[68:69], v[68:69], v[82:83] op_sel_hi:[1,0]
	v_pk_mul_f32 v[66:67], v[66:67], v[82:83] op_sel_hi:[1,0]
	v_pk_mul_f32 v[64:65], v[64:65], v[82:83] op_sel_hi:[1,0]
	v_max_f32_e32 v76, 0, v76
	v_max_f32_e32 v72, 0, v72
	v_max_f32_e32 v77, 0, v77
	v_max_f32_e32 v73, 0, v73
	v_max_f32_e32 v78, 0, v78
	v_max_f32_e32 v74, 0, v74
	v_max_f32_e32 v79, 0, v79
	v_max_f32_e32 v75, 0, v75
	v_max_f32_e32 v68, 0, v68
	v_max_f32_e32 v64, 0, v64
	v_max_f32_e32 v69, 0, v69
	v_max_f32_e32 v65, 0, v65
	v_max_f32_e32 v70, 0, v70
	v_max_f32_e32 v66, 0, v66
	v_max_f32_e32 v71, 0, v71
	v_max_f32_e32 v67, 0, v67
	v_pk_mul_f32 v[76:77], v[76:77], v[76:77]
	v_pk_mul_f32 v[72:73], v[72:73], v[72:73]
	v_pk_mul_f32 v[78:79], v[78:79], v[78:79]
	v_pk_mul_f32 v[74:75], v[74:75], v[74:75]
	v_pk_mul_f32 v[68:69], v[68:69], v[68:69]
	v_pk_mul_f32 v[82:83], v[64:65], v[64:65]
	v_pk_mul_f32 v[70:71], v[70:71], v[70:71]
	v_pk_mul_f32 v[84:85], v[66:67], v[66:67]
	v_cvt_pk_bf16_f32 v64, v76, v77
	v_cvt_pk_bf16_f32 v65, v78, v79
	v_cvt_pk_bf16_f32 v66, v72, v73
	v_cvt_pk_bf16_f32 v67, v74, v75
	v_cvt_pk_bf16_f32 v68, v68, v69
	v_cvt_pk_bf16_f32 v69, v70, v71
	v_cvt_pk_bf16_f32 v70, v82, v83
	v_cvt_pk_bf16_f32 v71, v84, v85
	global_store_dwordx4 v[80:81], v[64:67], off
	global_store_dwordx4 v[80:81], v[68:71], off offset:256
	s_nop 0
	v_lshl_add_u64 v[64:65], v[146:147], 0, s[8:9]
	s_nop 1
	s_waitcnt vmcnt(11)
; DI unsigned pk2(float a, float b) { f32x2 v = {a, b}; hbf2 r = __builtin_convertvector(v, hbf2); return __builtin_bit_cast(unsigned, r); }
;     DI void operator()(const f32x4 (&acc)[2][2][4][2], const Unit& u, int wr, int wc, int fr, int fq) const {
;     ...
; #pragma unroll
;         for (int ai = 0; ai < 2; ++ai)
; #pragma unroll
;             for (int m = 0; m < 4; ++m) {
;                 const int r = row0 + ai * 128 + m * 16;
;                 const float rstd = rsqrtf(ss[r] * (1.0f / 1024.0f) + EPS);
;                 bf16_t* rowp = HID + (size_t)r * 4096 + col0;
; #pragma unroll
;                 for (int bj = 0; bj < 2; ++bj) {
;                     f32x4 v0 = acc[ai][bj][m][0] * rstd, v1 = acc[ai][bj][m][1] * rstd;
; #pragma unroll
;                     for (int j = 0; j < 4; ++j) { float a = fmaxf(v0[j], 0.f), b = fmaxf(v1[j], 0.f); v0[j] = a * a; v1[j] = b * b; }
;                     u32x4 w; w.x = pk2(v0[0], v0[1]); w.y = pk2(v0[2], v0[3]); w.z = pk2(v1[0], v1[1]); w.w = pk2(v1[2], v1[3]);
;                     *(u32x4*)(rowp + bj * 128) = w;
;                 }
	v_mov_b32_e32 v66, v212
	v_fmamk_f32 v66, v66, 0x3a800000, v158
	v_mul_f32_e32 v67, 0x4b800000, v66
	v_cmp_gt_f32_e32 vcc, s50, v66
	s_nop 1
	v_cndmask_b32_e32 v66, v66, v67, vcc
	v_rsq_f32_e32 v68, v66
	v_add_co_u32_e64 v66, s[0:1], s51, v146
	v_mul_f32_e32 v69, 0x45800000, v68
	v_cndmask_b32_e32 v68, v68, v69, vcc
	v_pk_mul_f32 v[62:63], v[62:63], v[68:69] op_sel_hi:[1,0]
	v_pk_mul_f32 v[60:61], v[60:61], v[68:69] op_sel_hi:[1,0]
	v_pk_mul_f32 v[58:59], v[58:59], v[68:69] op_sel_hi:[1,0]
	v_pk_mul_f32 v[56:57], v[56:57], v[68:69] op_sel_hi:[1,0]
	v_pk_mul_f32 v[54:55], v[54:55], v[68:69] op_sel_hi:[1,0]
	v_pk_mul_f32 v[52:53], v[52:53], v[68:69] op_sel_hi:[1,0]
	v_pk_mul_f32 v[50:51], v[50:51], v[68:69] op_sel_hi:[1,0]
	v_pk_mul_f32 v[48:49], v[48:49], v[68:69] op_sel_hi:[1,0]
	v_max_f32_e32 v60, 0, v60
	v_max_f32_e32 v56, 0, v56
	v_max_f32_e32 v61, 0, v61
	v_max_f32_e32 v57, 0, v57
	v_max_f32_e32 v62, 0, v62
	v_max_f32_e32 v58, 0, v58
	v_max_f32_e32 v63, 0, v63
	v_max_f32_e32 v59, 0, v59
	v_max_f32_e32 v52, 0, v52
	v_max_f32_e32 v48, 0, v48
	v_max_f32_e32 v53, 0, v53
	v_max_f32_e32 v49, 0, v49
	v_max_f32_e32 v54, 0, v54
	v_max_f32_e32 v50, 0, v50
	v_max_f32_e32 v55, 0, v55
	v_max_f32_e32 v51, 0, v51
	v_pk_mul_f32 v[60:61], v[60:61], v[60:61]
	v_pk_mul_f32 v[56:57], v[56:57], v[56:57]
	v_pk_mul_f32 v[62:63], v[62:63], v[62:63]
	v_pk_mul_f32 v[58:59], v[58:59], v[58:59]
	v_addc_co_u32_e64 v67, s[0:1], 0, v147, s[0:1]
	v_pk_mul_f32 v[52:53], v[52:53], v[52:53]
	v_pk_mul_f32 v[68:69], v[48:49], v[48:49]
	v_pk_mul_f32 v[54:55], v[54:55], v[54:55]
	v_pk_mul_f32 v[70:71], v[50:51], v[50:51]
	v_cvt_pk_bf16_f32 v48, v60, v61
	v_cvt_pk_bf16_f32 v49, v62, v63
	v_cvt_pk_bf16_f32 v50, v56, v57
	v_cvt_pk_bf16_f32 v51, v58, v59
	v_cvt_pk_bf16_f32 v52, v52, v53
	v_cvt_pk_bf16_f32 v53, v54, v55
	v_cvt_pk_bf16_f32 v54, v68, v69
	v_cvt_pk_bf16_f32 v55, v70, v71
	global_store_dwordx4 v[66:67], v[48:51], off
	global_store_dwordx4 v[64:65], v[52:55], off offset:256
	s_nop 0
	v_lshl_add_u64 v[48:49], v[146:147], 0, s[12:13]
	s_nop 1
	s_waitcnt vmcnt(12)
	v_mov_b32_e32 v50, v213
	v_fmamk_f32 v50, v50, 0x3a800000, v158
	v_mul_f32_e32 v51, 0x4b800000, v50
	v_cmp_gt_f32_e32 vcc, s50, v50
	s_nop 1
	v_cndmask_b32_e32 v50, v50, v51, vcc
	v_rsq_f32_e32 v52, v50
	v_add_co_u32_e64 v50, s[0:1], s56, v146
	v_mul_f32_e32 v53, 0x45800000, v52
	v_cndmask_b32_e32 v52, v52, v53, vcc
	v_pk_mul_f32 v[46:47], v[46:47], v[52:53] op_sel_hi:[1,0]
	v_pk_mul_f32 v[44:45], v[44:45], v[52:53] op_sel_hi:[1,0]
	v_pk_mul_f32 v[42:43], v[42:43], v[52:53] op_sel_hi:[1,0]
	v_pk_mul_f32 v[40:41], v[40:41], v[52:53] op_sel_hi:[1,0]
	v_pk_mul_f32 v[38:39], v[38:39], v[52:53] op_sel_hi:[1,0]
	v_pk_mul_f32 v[36:37], v[36:37], v[52:53] op_sel_hi:[1,0]
	v_pk_mul_f32 v[34:35], v[34:35], v[52:53] op_sel_hi:[1,0]
	v_pk_mul_f32 v[32:33], v[32:33], v[52:53] op_sel_hi:[1,0]
	v_max_f32_e32 v44, 0, v44
	v_max_f32_e32 v40, 0, v40
	v_max_f32_e32 v45, 0, v45
	v_max_f32_e32 v41, 0, v41
	v_max_f32_e32 v46, 0, v46
	v_max_f32_e32 v42, 0, v42
	v_max_f32_e32 v47, 0, v47
	v_max_f32_e32 v43, 0, v43
	v_max_f32_e32 v36, 0, v36
	v_max_f32_e32 v32, 0, v32
	v_max_f32_e32 v37, 0, v37
	v_max_f32_e32 v33, 0, v33
	v_max_f32_e32 v38, 0, v38
	v_max_f32_e32 v34, 0, v34
	v_max_f32_e32 v39, 0, v39
	v_max_f32_e32 v35, 0, v35
	v_pk_mul_f32 v[44:45], v[44:45], v[44:45]
	v_pk_mul_f32 v[40:41], v[40:41], v[40:41]
	v_pk_mul_f32 v[46:47], v[46:47], v[46:47]
	v_pk_mul_f32 v[42:43], v[42:43], v[42:43]
	v_addc_co_u32_e64 v51, s[0:1], 0, v147, s[0:1]
	v_pk_mul_f32 v[36:37], v[36:37], v[36:37]
	v_pk_mul_f32 v[52:53], v[32:33], v[32:33]
	v_pk_mul_f32 v[38:39], v[38:39], v[38:39]
	v_pk_mul_f32 v[54:55], v[34:35], v[34:35]
	v_cvt_pk_bf16_f32 v32, v44, v45
	v_cvt_pk_bf16_f32 v33, v46, v47
	v_cvt_pk_bf16_f32 v34, v40, v41
	v_cvt_pk_bf16_f32 v35, v42, v43
	v_cvt_pk_bf16_f32 v36, v36, v37
	v_cvt_pk_bf16_f32 v37, v38, v39
	v_cvt_pk_bf16_f32 v38, v52, v53
	v_cvt_pk_bf16_f32 v39, v54, v55
	global_store_dwordx4 v[50:51], v[32:35], off
	global_store_dwordx4 v[48:49], v[36:39], off offset:256
	s_nop 0
	v_lshl_add_u64 v[32:33], v[146:147], 0, s[14:15]
	s_nop 1
	s_waitcnt vmcnt(13)
; DI unsigned pk2(float a, float b) { f32x2 v = {a, b}; hbf2 r = __builtin_convertvector(v, hbf2); return __builtin_bit_cast(unsigned, r); }
; #define PG8_WAIT_V(n) asm volatile("s_waitcnt vmcnt(" #n ")" ::: "memory")
; #define PG8_BAR __builtin_amdgcn_s_barrier()
; template <class Epi>
; __device__ __forceinline__ void gemm_phase(LAS unsigned char* lds, const Gemm g, const StaticOrder& S, const Epi& E) {
;     ...
;     PG8_WAIT_V(0);
;     if (wr == 0) PG8_BAR;
;     PG8_BAR;
;     DI void operator()(const f32x4 (&acc)[2][2][4][2], const Unit& u, int wr, int wc, int fr, int fq) const {
;     ...
; #pragma unroll
;         for (int ai = 0; ai < 2; ++ai)
; #pragma unroll
;             for (int m = 0; m < 4; ++m) {
;                 const int r = row0 + ai * 128 + m * 16;
;                 const float rstd = rsqrtf(ss[r] * (1.0f / 1024.0f) + EPS);
;                 bf16_t* rowp = HID + (size_t)r * 4096 + col0;
; #pragma unroll
;                 for (int bj = 0; bj < 2; ++bj) {
;                     f32x4 v0 = acc[ai][bj][m][0] * rstd, v1 = acc[ai][bj][m][1] * rstd;
; #pragma unroll
;                     for (int j = 0; j < 4; ++j) { float a = fmaxf(v0[j], 0.f), b = fmaxf(v1[j], 0.f); v0[j] = a * a; v1[j] = b * b; }
;                     u32x4 w; w.x = pk2(v0[0], v0[1]); w.y = pk2(v0[2], v0[3]); w.z = pk2(v1[0], v1[1]); w.w = pk2(v1[2], v1[3]);
;                     *(u32x4*)(rowp + bj * 128) = w;
;                 }
	v_mov_b32_e32 v34, v214
	v_fmamk_f32 v34, v34, 0x3a800000, v158
	v_mul_f32_e32 v35, 0x4b800000, v34
	v_cmp_gt_f32_e32 vcc, s50, v34
	s_nop 1
	v_cndmask_b32_e32 v34, v34, v35, vcc
	v_rsq_f32_e32 v36, v34
	v_add_co_u32_e64 v34, s[0:1], s57, v146
	v_mul_f32_e32 v37, 0x45800000, v36
	v_cndmask_b32_e32 v36, v36, v37, vcc
	v_pk_mul_f32 v[30:31], v[30:31], v[36:37] op_sel_hi:[1,0]
	v_pk_mul_f32 v[28:29], v[28:29], v[36:37] op_sel_hi:[1,0]
	v_pk_mul_f32 v[26:27], v[26:27], v[36:37] op_sel_hi:[1,0]
	v_pk_mul_f32 v[24:25], v[24:25], v[36:37] op_sel_hi:[1,0]
	v_pk_mul_f32 v[22:23], v[22:23], v[36:37] op_sel_hi:[1,0]
	v_pk_mul_f32 v[20:21], v[20:21], v[36:37] op_sel_hi:[1,0]
	v_pk_mul_f32 v[18:19], v[18:19], v[36:37] op_sel_hi:[1,0]
	v_pk_mul_f32 v[16:17], v[16:17], v[36:37] op_sel_hi:[1,0]
	v_max_f32_e32 v28, 0, v28
	v_max_f32_e32 v24, 0, v24
	v_max_f32_e32 v29, 0, v29
	v_max_f32_e32 v25, 0, v25
	v_max_f32_e32 v30, 0, v30
	v_max_f32_e32 v26, 0, v26
	v_max_f32_e32 v31, 0, v31
	v_max_f32_e32 v27, 0, v27
	v_max_f32_e32 v20, 0, v20
	v_max_f32_e32 v16, 0, v16
	v_max_f32_e32 v21, 0, v21
	v_max_f32_e32 v17, 0, v17
	v_max_f32_e32 v22, 0, v22
	v_max_f32_e32 v18, 0, v18
	v_max_f32_e32 v23, 0, v23
	v_max_f32_e32 v19, 0, v19
	v_pk_mul_f32 v[28:29], v[28:29], v[28:29]
	v_pk_mul_f32 v[24:25], v[24:25], v[24:25]
	v_pk_mul_f32 v[30:31], v[30:31], v[30:31]
	v_pk_mul_f32 v[26:27], v[26:27], v[26:27]
	v_addc_co_u32_e64 v35, s[0:1], 0, v147, s[0:1]
	v_pk_mul_f32 v[20:21], v[20:21], v[20:21]
	v_pk_mul_f32 v[36:37], v[16:17], v[16:17]
	v_pk_mul_f32 v[22:23], v[22:23], v[22:23]
	v_pk_mul_f32 v[38:39], v[18:19], v[18:19]
	v_cvt_pk_bf16_f32 v16, v28, v29
	v_cvt_pk_bf16_f32 v17, v30, v31
	v_cvt_pk_bf16_f32 v18, v24, v25
	v_cvt_pk_bf16_f32 v19, v26, v27
	v_cvt_pk_bf16_f32 v20, v20, v21
	v_cvt_pk_bf16_f32 v21, v22, v23
	v_cvt_pk_bf16_f32 v22, v36, v37
	v_cvt_pk_bf16_f32 v23, v38, v39
	global_store_dwordx4 v[34:35], v[16:19], off
	global_store_dwordx4 v[32:33], v[20:23], off offset:256
	s_nop 0
	s_and_b64 vcc, exec, s[4:5]
	v_lshl_add_u64 v[16:17], v[146:147], 0, s[18:19]
	s_nop 1
	s_waitcnt vmcnt(14)
	v_mov_b32_e32 v18, v215
	v_fmamk_f32 v18, v18, 0x3a800000, v158
	v_mul_f32_e32 v19, 0x4b800000, v18
	v_cmp_gt_f32_e64 s[0:1], s50, v18
	s_nop 1
	v_cndmask_b32_e64 v18, v18, v19, s[0:1]
	v_rsq_f32_e32 v20, v18
	v_add_co_u32_e64 v18, s[4:5], s58, v146
	v_mul_f32_e32 v21, 0x45800000, v20
	v_cndmask_b32_e64 v20, v20, v21, s[0:1]
	v_pk_mul_f32 v[14:15], v[14:15], v[20:21] op_sel_hi:[1,0]
	v_pk_mul_f32 v[12:13], v[12:13], v[20:21] op_sel_hi:[1,0]
	v_pk_mul_f32 v[10:11], v[10:11], v[20:21] op_sel_hi:[1,0]
	v_pk_mul_f32 v[8:9], v[8:9], v[20:21] op_sel_hi:[1,0]
	v_pk_mul_f32 v[6:7], v[6:7], v[20:21] op_sel_hi:[1,0]
	v_pk_mul_f32 v[4:5], v[4:5], v[20:21] op_sel_hi:[1,0]
	v_pk_mul_f32 v[2:3], v[2:3], v[20:21] op_sel_hi:[1,0]
	v_pk_mul_f32 v[0:1], v[0:1], v[20:21] op_sel_hi:[1,0]
	v_max_f32_e32 v12, 0, v12
	v_max_f32_e32 v8, 0, v8
	v_max_f32_e32 v13, 0, v13
	v_max_f32_e32 v9, 0, v9
	v_max_f32_e32 v14, 0, v14
	v_max_f32_e32 v10, 0, v10
	v_max_f32_e32 v15, 0, v15
	v_max_f32_e32 v11, 0, v11
	v_max_f32_e32 v4, 0, v4
	v_max_f32_e32 v0, 0, v0
	v_max_f32_e32 v5, 0, v5
	v_max_f32_e32 v1, 0, v1
	v_max_f32_e32 v6, 0, v6
	v_max_f32_e32 v2, 0, v2
	v_max_f32_e32 v7, 0, v7
	v_max_f32_e32 v3, 0, v3
	v_pk_mul_f32 v[12:13], v[12:13], v[12:13]
	v_pk_mul_f32 v[8:9], v[8:9], v[8:9]
	v_pk_mul_f32 v[14:15], v[14:15], v[14:15]
	v_pk_mul_f32 v[10:11], v[10:11], v[10:11]
	v_addc_co_u32_e64 v19, s[4:5], 0, v147, s[4:5]
	v_pk_mul_f32 v[4:5], v[4:5], v[4:5]
	v_pk_mul_f32 v[20:21], v[0:1], v[0:1]
	v_pk_mul_f32 v[6:7], v[6:7], v[6:7]
	v_pk_mul_f32 v[22:23], v[2:3], v[2:3]
	v_cvt_pk_bf16_f32 v0, v12, v13
	v_cvt_pk_bf16_f32 v1, v14, v15
	v_cvt_pk_bf16_f32 v2, v8, v9
	v_cvt_pk_bf16_f32 v3, v10, v11
	v_cvt_pk_bf16_f32 v4, v4, v5
	v_cvt_pk_bf16_f32 v5, v6, v7
	v_cvt_pk_bf16_f32 v6, v20, v21
	v_cvt_pk_bf16_f32 v7, v22, v23
	global_store_dwordx4 v[18:19], v[0:3], off
	global_store_dwordx4 v[16:17], v[4:7], off offset:256
	s_cbranch_vccz .LBB0_1457
	s_waitcnt vmcnt(0)
	s_cmpk_gt_u32 s2, 0xff
	s_cbranch_scc1 .LBB0_1468
	s_barrier
